# v37 + SGPR-base (saddr) form for 32 K-loop LDS-DMA tile loads, their v_lshl_add_u64 dropped
# speedup vs baseline: 1.0050x; 1.0039x over previous
; #define PG8_STAGE(bufoff, gbase, voff) do { _Pragma("unroll") for (int _i = 0; _i < 2; ++_i) \
;         __builtin_amdgcn_global_load_lds((const unsigned*)((const char*)(gbase) + (voff)[_i]), (LAS unsigned*)(lds + (bufoff) + ldsw + _i * 8192), 16, 0, 0); } while (0)
; #define PG8_LDA(dst, b, h) do { _Pragma("unroll") for (int m = 0; m < 4; ++m) _Pragma("unroll") for (int k = 0; k < 2; ++k) dst[m][k] = *(const LAS bf16x8*)(lds + PG8_SA(b, h) + aoff + m * 2048 + k * 1024); } while (0)
; #define PG8_LDB(dst, b, h) do { _Pragma("unroll") for (int n = 0; n < 2; ++n) _Pragma("unroll") for (int k = 0; k < 2; ++k) dst[n][k] = *(const LAS bf16x8*)(lds + PG8_SB(b, h) + boff + n * 2048 + k * 1024); } while (0)
; #define PG8_MMA(ai, bj, At, Bt) do { __builtin_amdgcn_s_setprio(1); _Pragma("unroll") for (int m = 0; m < 4; ++m) _Pragma("unroll") for (int n = 0; n < 2; ++n) _Pragma("unroll") for (int k = 0; k < 2; ++k) \
;         acc[ai][bj][m][n] = __builtin_amdgcn_mfma_f32_16x16x32_bf16(Bt[n][k], At[m][k], acc[ai][bj][m][n], 0, 0, 0); __builtin_amdgcn_s_setprio(0); } while (0)
; #define PG8_WAIT_V(n) asm volatile("s_waitcnt vmcnt(" #n ")" ::: "memory")
; #define PG8_WAIT_L(n) asm volatile("s_waitcnt lgkmcnt(" #n ")" ::: "memory")
; #define PG8_BAR __builtin_amdgcn_s_barrier()
; template <class Epi, class Sched>
; __device__ __forceinline__ void gemm_phase(LAS unsigned char* lds, const Gemm g, const Sched& S, const Epi& E) {
;     ...
;         for (int t = 0; t < nt; t += 2) {
;             const bool last = (t == nt - 2);
;             const char* a1 = cA + (size_t)(t + 1) * kstep;
;             const char* a2 = last ? nA : cA + (size_t)(t + 2) * kstep; const char* b2 = last ? nB : cB + (size_t)(t + 2) * kstep;
;             const char* a3 = a2 + kstep; const char* b3 = b2 + kstep;
;             if (last && has_next) S.a_ready(nxt);
;             PG8_LDB(B0, 0, 0); PG8_LDB(B1, 0, 1); PG8_SCHED; PG8_LDA(At, 0, 0); PG8_STAGE(PG8_SA(1, 1), a1 + hstepA, voffA);
;             PG8_WAIT_V(8); PG8_WAIT_L(0); PG8_BAR; PG8_MMA(0, 0, At, B0); PG8_MMA(0, 1, At, B1); PG8_BAR; PG8_SCHED;
;             PG8_LDA(At, 0, 1); PG8_STAGE(PG8_SB(0, 0), b2, voffB); PG8_STAGE(PG8_SB(0, 1), b2 + hstepB, voffB); PG8_STAGE(PG8_SA(0, 0), a2, voffA);
;             PG8_WAIT_V(8); PG8_WAIT_L(0); PG8_BAR; PG8_MMA(1, 0, At, B0); PG8_MMA(1, 1, At, B1); PG8_BAR; PG8_SCHED;
.LBB0_137:
	s_add_u32 s28, s26, 0xfff80080
	s_addc_u32 s29, s27, -1
	s_add_i32 s60, 0, 0x10000
	s_cmp_eq_u32 s59, 28
	s_cselect_b32 s41, s21, s29
	s_cselect_b32 s40, s55, s28
	s_cselect_b32 s29, s19, s58
	s_cselect_b32 s28, s56, s57
	s_add_i32 s62, 0, 0x14000
	v_add_u32_e32 v154, s60, v159
	v_add_u32_e32 v174, s62, v159
	ds_read_b128 v[142:145], v154
	ds_read_b128 v[146:149], v154 offset:1024
	ds_read_b128 v[150:153], v154 offset:2048
	ds_read_b128 v[154:157], v154 offset:3072
	ds_read_b128 v[162:165], v174
	ds_read_b128 v[166:169], v174 offset:1024
	ds_read_b128 v[170:173], v174 offset:2048
	ds_read_b128 v[174:177], v174 offset:3072
	s_add_i32 m0, s46, 0xc000
	ds_read_b128 v[178:181], v161
	ds_read_b128 v[182:185], v161 offset:1024
	ds_read_b128 v[186:189], v161 offset:2048
	ds_read_b128 v[190:193], v161 offset:3072
	ds_read_b128 v[194:197], v161 offset:4096
	ds_read_b128 v[212:215], v161 offset:5120
	ds_read_b128 v[216:219], v161 offset:6144
	ds_read_b128 v[220:223], v161 offset:7168
	global_load_lds_dwordx4 v138, s[26:27]
	s_add_i32 m0, s46, 0xe000
	s_nop 0
	global_load_lds_dwordx4 v140, s[26:27]
	s_waitcnt vmcnt(8)
	s_waitcnt lgkmcnt(0)
	s_barrier
	s_waitcnt lgkmcnt(0)
	v_mfma_f32_16x16x32_bf16 v[130:133], v[142:145], v[178:181], v[130:133]
	v_mfma_f32_16x16x32_bf16 v[122:125], v[150:153], v[178:181], v[122:125]
	v_mfma_f32_16x16x32_bf16 v[114:117], v[142:145], v[186:189], v[114:117]
	v_mfma_f32_16x16x32_bf16 v[106:109], v[150:153], v[186:189], v[106:109]
	v_mfma_f32_16x16x32_bf16 v[98:101], v[142:145], v[194:197], v[98:101]
	v_mfma_f32_16x16x32_bf16 v[90:93], v[150:153], v[194:197], v[90:93]
	v_mfma_f32_16x16x32_bf16 v[82:85], v[142:145], v[216:219], v[82:85]
	v_mfma_f32_16x16x32_bf16 v[74:77], v[150:153], v[216:219], v[74:77]
	v_mfma_f32_16x16x32_bf16 v[130:133], v[146:149], v[182:185], v[130:133]
	v_mfma_f32_16x16x32_bf16 v[122:125], v[154:157], v[182:185], v[122:125]
	v_mfma_f32_16x16x32_bf16 v[114:117], v[146:149], v[190:193], v[114:117]
	v_mfma_f32_16x16x32_bf16 v[106:109], v[154:157], v[190:193], v[106:109]
	v_mfma_f32_16x16x32_bf16 v[98:101], v[146:149], v[212:215], v[98:101]
	v_mfma_f32_16x16x32_bf16 v[90:93], v[154:157], v[212:215], v[90:93]
	v_mfma_f32_16x16x32_bf16 v[82:85], v[146:149], v[220:223], v[82:85]
	v_mfma_f32_16x16x32_bf16 v[74:77], v[154:157], v[220:223], v[74:77]
	v_mfma_f32_16x16x32_bf16 v[126:129], v[162:165], v[178:181], v[126:129]
	v_mfma_f32_16x16x32_bf16 v[118:121], v[170:173], v[178:181], v[118:121]
	v_mfma_f32_16x16x32_bf16 v[110:113], v[162:165], v[186:189], v[110:113]
	v_mfma_f32_16x16x32_bf16 v[102:105], v[170:173], v[186:189], v[102:105]
	v_mfma_f32_16x16x32_bf16 v[94:97], v[162:165], v[194:197], v[94:97]
	v_mfma_f32_16x16x32_bf16 v[86:89], v[170:173], v[194:197], v[86:89]
	v_mfma_f32_16x16x32_bf16 v[78:81], v[162:165], v[216:219], v[78:81]
	v_mfma_f32_16x16x32_bf16 v[70:73], v[170:173], v[216:219], v[70:73]
	v_mfma_f32_16x16x32_bf16 v[126:129], v[166:169], v[182:185], v[126:129]
	v_mfma_f32_16x16x32_bf16 v[118:121], v[174:177], v[182:185], v[118:121]
	v_mfma_f32_16x16x32_bf16 v[110:113], v[166:169], v[190:193], v[110:113]
	v_mfma_f32_16x16x32_bf16 v[102:105], v[174:177], v[190:193], v[102:105]
	v_mfma_f32_16x16x32_bf16 v[94:97], v[166:169], v[212:215], v[94:97]
	v_mfma_f32_16x16x32_bf16 v[86:89], v[174:177], v[212:215], v[86:89]
	v_mfma_f32_16x16x32_bf16 v[78:81], v[166:169], v[220:223], v[78:81]
	v_mfma_f32_16x16x32_bf16 v[70:73], v[174:177], v[220:223], v[70:73]
	s_barrier
	s_add_i32 s60, s60, s45
	v_lshl_add_u64 v[224:225], s[28:29], 0, v[4:5]
	s_mov_b32 m0, s60
	ds_read_b128 v[178:181], v161 offset:16384
	ds_read_b128 v[182:185], v161 offset:17408
	ds_read_b128 v[186:189], v161 offset:18432
	ds_read_b128 v[190:193], v161 offset:19456
	ds_read_b128 v[194:197], v161 offset:20480
	ds_read_b128 v[212:215], v161 offset:21504
	ds_read_b128 v[216:219], v161 offset:22528
	ds_read_b128 v[220:223], v161 offset:23552
	global_load_lds_dwordx4 v[224:225], off
	s_add_i32 m0, s60, 0x2000
	s_add_u32 s60, s28, 0x80000
	v_lshl_add_u64 v[226:227], s[28:29], 0, v[2:3]
	s_addc_u32 s61, s29, 0
	s_add_i32 s62, s62, s45
	global_load_lds_dwordx4 v[226:227], off
	s_mov_b32 m0, s62
	v_lshl_add_u64 v[230:231], s[40:41], 0, v[134:135]
	global_load_lds_dwordx4 v4, s[60:61]
	s_add_i32 m0, s62, 0x2000
	s_nop 0
	global_load_lds_dwordx4 v2, s[60:61]
	v_lshl_add_u64 v[228:229], s[40:41], 0, v[136:137]
	s_mov_b32 m0, s46
	s_nop 0
	global_load_lds_dwordx4 v[228:229], off
	s_mov_b32 m0, s47
	s_nop 0
	global_load_lds_dwordx4 v[230:231], off
	s_waitcnt vmcnt(8)
	s_waitcnt lgkmcnt(0)
	s_barrier
; #define PG8_STAGE(bufoff, gbase, voff) do { _Pragma("unroll") for (int _i = 0; _i < 2; ++_i) \
;         __builtin_amdgcn_global_load_lds((const unsigned*)((const char*)(gbase) + (voff)[_i]), (LAS unsigned*)(lds + (bufoff) + ldsw + _i * 8192), 16, 0, 0); } while (0)
; #define PG8_LDA(dst, b, h) do { _Pragma("unroll") for (int m = 0; m < 4; ++m) _Pragma("unroll") for (int k = 0; k < 2; ++k) dst[m][k] = *(const LAS bf16x8*)(lds + PG8_SA(b, h) + aoff + m * 2048 + k * 1024); } while (0)
; #define PG8_LDB(dst, b, h) do { _Pragma("unroll") for (int n = 0; n < 2; ++n) _Pragma("unroll") for (int k = 0; k < 2; ++k) dst[n][k] = *(const LAS bf16x8*)(lds + PG8_SB(b, h) + boff + n * 2048 + k * 1024); } while (0)
; #define PG8_MMA(ai, bj, At, Bt) do { __builtin_amdgcn_s_setprio(1); _Pragma("unroll") for (int m = 0; m < 4; ++m) _Pragma("unroll") for (int n = 0; n < 2; ++n) _Pragma("unroll") for (int k = 0; k < 2; ++k) \
;         acc[ai][bj][m][n] = __builtin_amdgcn_mfma_f32_16x16x32_bf16(Bt[n][k], At[m][k], acc[ai][bj][m][n], 0, 0, 0); __builtin_amdgcn_s_setprio(0); } while (0)
; #define PG8_WAIT_V(n) asm volatile("s_waitcnt vmcnt(" #n ")" ::: "memory")
; #define PG8_WAIT_L(n) asm volatile("s_waitcnt lgkmcnt(" #n ")" ::: "memory")
; #define PG8_BAR __builtin_amdgcn_s_barrier()
; #define PG8_SCHED __builtin_amdgcn_sched_barrier(0)
; template <class Epi, class Sched>
; __device__ __forceinline__ void gemm_phase(LAS unsigned char* lds, const Gemm g, const Sched& S, const Epi& E) {
;     ...
;             PG8_WAIT_V(8); PG8_WAIT_L(0); PG8_BAR; PG8_MMA(1, 0, At, B0); PG8_MMA(1, 1, At, B1); PG8_BAR; PG8_SCHED;
;             PG8_LDB(B0, 1, 0); PG8_LDB(B1, 1, 1); PG8_SCHED; PG8_LDA(At, 1, 0); PG8_STAGE(PG8_SA(0, 1), a2 + hstepA, voffA);
;             PG8_WAIT_V(8); PG8_WAIT_L(0); PG8_BAR; PG8_MMA(0, 0, At, B0); PG8_MMA(0, 1, At, B1); PG8_BAR; PG8_SCHED;
	s_waitcnt lgkmcnt(0)
	v_mfma_f32_16x16x32_bf16 v[66:69], v[142:145], v[178:181], v[66:69]
	v_mfma_f32_16x16x32_bf16 v[58:61], v[150:153], v[178:181], v[58:61]
	v_mfma_f32_16x16x32_bf16 v[50:53], v[142:145], v[186:189], v[50:53]
	v_mfma_f32_16x16x32_bf16 v[42:45], v[150:153], v[186:189], v[42:45]
	v_mfma_f32_16x16x32_bf16 v[34:37], v[142:145], v[194:197], v[34:37]
	v_mfma_f32_16x16x32_bf16 v[26:29], v[150:153], v[194:197], v[26:29]
	v_mfma_f32_16x16x32_bf16 v[18:21], v[142:145], v[216:219], v[18:21]
	v_mfma_f32_16x16x32_bf16 v[10:13], v[150:153], v[216:219], v[10:13]
	v_mfma_f32_16x16x32_bf16 v[66:69], v[146:149], v[182:185], v[66:69]
	v_mfma_f32_16x16x32_bf16 v[58:61], v[154:157], v[182:185], v[58:61]
	v_mfma_f32_16x16x32_bf16 v[50:53], v[146:149], v[190:193], v[50:53]
	v_mfma_f32_16x16x32_bf16 v[42:45], v[154:157], v[190:193], v[42:45]
	v_mfma_f32_16x16x32_bf16 v[34:37], v[146:149], v[212:215], v[34:37]
	v_mfma_f32_16x16x32_bf16 v[26:29], v[154:157], v[212:215], v[26:29]
	v_mfma_f32_16x16x32_bf16 v[18:21], v[146:149], v[220:223], v[18:21]
	v_mfma_f32_16x16x32_bf16 v[10:13], v[154:157], v[220:223], v[10:13]
	v_mfma_f32_16x16x32_bf16 v[62:65], v[162:165], v[178:181], v[62:65]
	v_mfma_f32_16x16x32_bf16 v[54:57], v[170:173], v[178:181], v[54:57]
	v_mfma_f32_16x16x32_bf16 v[46:49], v[162:165], v[186:189], v[46:49]
	v_mfma_f32_16x16x32_bf16 v[38:41], v[170:173], v[186:189], v[38:41]
	v_mfma_f32_16x16x32_bf16 v[30:33], v[162:165], v[194:197], v[30:33]
	v_mfma_f32_16x16x32_bf16 v[22:25], v[170:173], v[194:197], v[22:25]
	v_mfma_f32_16x16x32_bf16 v[14:17], v[162:165], v[216:219], v[14:17]
	v_mfma_f32_16x16x32_bf16 v[6:9], v[170:173], v[216:219], v[6:9]
	v_mfma_f32_16x16x32_bf16 v[62:65], v[166:169], v[182:185], v[62:65]
	v_mfma_f32_16x16x32_bf16 v[54:57], v[174:177], v[182:185], v[54:57]
	v_mfma_f32_16x16x32_bf16 v[46:49], v[166:169], v[190:193], v[46:49]
	v_mfma_f32_16x16x32_bf16 v[38:41], v[174:177], v[190:193], v[38:41]
	v_mfma_f32_16x16x32_bf16 v[30:33], v[166:169], v[212:215], v[30:33]
	v_mfma_f32_16x16x32_bf16 v[22:25], v[174:177], v[212:215], v[22:25]
	v_mfma_f32_16x16x32_bf16 v[14:17], v[166:169], v[220:223], v[14:17]
	v_mfma_f32_16x16x32_bf16 v[6:9], v[174:177], v[220:223], v[6:9]
	s_barrier
	s_add_i32 s60, 0, 0x18000
	s_add_i32 s61, 0, 0x1c000
	v_add_u32_e32 v154, s60, v159
	v_add_u32_e32 v174, s61, v159
	ds_read_b128 v[142:145], v154
	ds_read_b128 v[146:149], v154 offset:1024
	ds_read_b128 v[150:153], v154 offset:2048
	ds_read_b128 v[154:157], v154 offset:3072
	ds_read_b128 v[162:165], v174
	ds_read_b128 v[166:169], v174 offset:1024
	ds_read_b128 v[170:173], v174 offset:2048
	ds_read_b128 v[174:177], v174 offset:3072
	s_add_u32 s40, s40, 0x80000
	s_addc_u32 s41, s41, 0
	s_mov_b32 m0, s48
	ds_read_b128 v[178:181], v161 offset:32768
	ds_read_b128 v[182:185], v161 offset:33792
	ds_read_b128 v[186:189], v161 offset:34816
	ds_read_b128 v[190:193], v161 offset:35840
	ds_read_b128 v[194:197], v161 offset:36864
	ds_read_b128 v[212:215], v161 offset:37888
	ds_read_b128 v[216:219], v161 offset:38912
	ds_read_b128 v[220:223], v161 offset:39936
	global_load_lds_dwordx4 v136, s[40:41]
	s_mov_b32 m0, s49
	s_nop 0
	global_load_lds_dwordx4 v134, s[40:41]
	s_waitcnt vmcnt(8)
	s_waitcnt lgkmcnt(0)
	s_barrier
	s_waitcnt lgkmcnt(0)
	v_mfma_f32_16x16x32_bf16 v[130:133], v[142:145], v[178:181], v[130:133]
	v_mfma_f32_16x16x32_bf16 v[122:125], v[150:153], v[178:181], v[122:125]
	v_mfma_f32_16x16x32_bf16 v[114:117], v[142:145], v[186:189], v[114:117]
	v_mfma_f32_16x16x32_bf16 v[106:109], v[150:153], v[186:189], v[106:109]
	v_mfma_f32_16x16x32_bf16 v[98:101], v[142:145], v[194:197], v[98:101]
	v_mfma_f32_16x16x32_bf16 v[90:93], v[150:153], v[194:197], v[90:93]
	v_mfma_f32_16x16x32_bf16 v[82:85], v[142:145], v[216:219], v[82:85]
	v_mfma_f32_16x16x32_bf16 v[74:77], v[150:153], v[216:219], v[74:77]
	v_mfma_f32_16x16x32_bf16 v[130:133], v[146:149], v[182:185], v[130:133]
	v_mfma_f32_16x16x32_bf16 v[122:125], v[154:157], v[182:185], v[122:125]
	v_mfma_f32_16x16x32_bf16 v[114:117], v[146:149], v[190:193], v[114:117]
	v_mfma_f32_16x16x32_bf16 v[106:109], v[154:157], v[190:193], v[106:109]
	v_mfma_f32_16x16x32_bf16 v[98:101], v[146:149], v[212:215], v[98:101]
	v_mfma_f32_16x16x32_bf16 v[90:93], v[154:157], v[212:215], v[90:93]
	v_mfma_f32_16x16x32_bf16 v[82:85], v[146:149], v[220:223], v[82:85]
	v_mfma_f32_16x16x32_bf16 v[74:77], v[154:157], v[220:223], v[74:77]
	v_mfma_f32_16x16x32_bf16 v[126:129], v[162:165], v[178:181], v[126:129]
	v_mfma_f32_16x16x32_bf16 v[118:121], v[170:173], v[178:181], v[118:121]
	v_mfma_f32_16x16x32_bf16 v[110:113], v[162:165], v[186:189], v[110:113]
	v_mfma_f32_16x16x32_bf16 v[102:105], v[170:173], v[186:189], v[102:105]
	v_mfma_f32_16x16x32_bf16 v[94:97], v[162:165], v[194:197], v[94:97]
	v_mfma_f32_16x16x32_bf16 v[86:89], v[170:173], v[194:197], v[86:89]
	v_mfma_f32_16x16x32_bf16 v[78:81], v[162:165], v[216:219], v[78:81]
	v_mfma_f32_16x16x32_bf16 v[70:73], v[170:173], v[216:219], v[70:73]
	v_mfma_f32_16x16x32_bf16 v[126:129], v[166:169], v[182:185], v[126:129]
	v_mfma_f32_16x16x32_bf16 v[118:121], v[174:177], v[182:185], v[118:121]
	v_mfma_f32_16x16x32_bf16 v[110:113], v[166:169], v[190:193], v[110:113]
	v_mfma_f32_16x16x32_bf16 v[102:105], v[174:177], v[190:193], v[102:105]
	v_mfma_f32_16x16x32_bf16 v[94:97], v[166:169], v[212:215], v[94:97]
	v_mfma_f32_16x16x32_bf16 v[86:89], v[174:177], v[212:215], v[86:89]
	v_mfma_f32_16x16x32_bf16 v[78:81], v[166:169], v[220:223], v[78:81]
	v_mfma_f32_16x16x32_bf16 v[70:73], v[174:177], v[220:223], v[70:73]
	s_barrier
; #define PG8_STAGE(bufoff, gbase, voff) do { _Pragma("unroll") for (int _i = 0; _i < 2; ++_i) \
;         __builtin_amdgcn_global_load_lds((const unsigned*)((const char*)(gbase) + (voff)[_i]), (LAS unsigned*)(lds + (bufoff) + ldsw + _i * 8192), 16, 0, 0); } while (0)
; #define PG8_LDA(dst, b, h) do { _Pragma("unroll") for (int m = 0; m < 4; ++m) _Pragma("unroll") for (int k = 0; k < 2; ++k) dst[m][k] = *(const LAS bf16x8*)(lds + PG8_SA(b, h) + aoff + m * 2048 + k * 1024); } while (0)
; #define PG8_MMA(ai, bj, At, Bt) do { __builtin_amdgcn_s_setprio(1); _Pragma("unroll") for (int m = 0; m < 4; ++m) _Pragma("unroll") for (int n = 0; n < 2; ++n) _Pragma("unroll") for (int k = 0; k < 2; ++k) \
;         acc[ai][bj][m][n] = __builtin_amdgcn_mfma_f32_16x16x32_bf16(Bt[n][k], At[m][k], acc[ai][bj][m][n], 0, 0, 0); __builtin_amdgcn_s_setprio(0); } while (0)
; #define PG8_WAIT_V(n) asm volatile("s_waitcnt vmcnt(" #n ")" ::: "memory")
; #define PG8_WAIT_L(n) asm volatile("s_waitcnt lgkmcnt(" #n ")" ::: "memory")
; #define PG8_BAR __builtin_amdgcn_s_barrier()
; #define PG8_SCHED __builtin_amdgcn_sched_barrier(0)
; template <class Epi, class Sched>
; __device__ __forceinline__ void gemm_phase(LAS unsigned char* lds, const Gemm g, const Sched& S, const Epi& E) {
;     ...
;             PG8_LDA(At, 1, 1); PG8_STAGE(PG8_SB(1, 0), b3, voffB); PG8_STAGE(PG8_SB(1, 1), b3 + hstepB, voffB); PG8_STAGE(PG8_SA(1, 0), a3, voffA);
;             PG8_WAIT_V(8); PG8_WAIT_L(0); PG8_BAR; PG8_MMA(1, 0, At, B0); PG8_MMA(1, 1, At, B1); PG8_BAR; PG8_SCHED;
;         }
;         if (wr == 0) PG8_BAR;
	s_add_i32 s40, s60, s45
	v_lshl_add_u64 v[224:225], v[224:225], 0, s[36:37]
	s_mov_b32 m0, s40
	ds_read_b128 v[178:181], v161 offset:49152
	ds_read_b128 v[182:185], v161 offset:50176
	ds_read_b128 v[186:189], v161 offset:51200
	ds_read_b128 v[190:193], v161 offset:52224
	ds_read_b128 v[194:197], v161 offset:53248
	ds_read_b128 v[212:215], v161 offset:54272
	ds_read_b128 v[216:219], v161 offset:55296
	ds_read_b128 v[220:223], v161 offset:56320
	global_load_lds_dwordx4 v[224:225], off
	s_add_i32 m0, s40, 0x2000
	s_add_u32 s28, s28, 0x80080
	v_lshl_add_u64 v[224:225], v[226:227], 0, s[36:37]
	s_addc_u32 s29, s29, 0
	s_add_i32 s40, s61, s45
	global_load_lds_dwordx4 v[224:225], off
	s_mov_b32 m0, s40
	s_nop 0
	global_load_lds_dwordx4 v4, s[28:29]
	s_add_i32 m0, s40, 0x2000
	s_nop 0
	global_load_lds_dwordx4 v2, s[28:29]
	v_lshl_add_u64 v[224:225], v[228:229], 0, s[36:37]
	s_mov_b32 m0, s50
	s_nop 0
	global_load_lds_dwordx4 v[224:225], off
	v_lshl_add_u64 v[224:225], v[230:231], 0, s[36:37]
	s_mov_b32 m0, s51
	s_nop 0
	global_load_lds_dwordx4 v[224:225], off
	s_waitcnt vmcnt(8)
	s_waitcnt lgkmcnt(0)
	s_barrier
	s_waitcnt lgkmcnt(0)
	v_mfma_f32_16x16x32_bf16 v[66:69], v[142:145], v[178:181], v[66:69]
	v_mfma_f32_16x16x32_bf16 v[58:61], v[150:153], v[178:181], v[58:61]
	v_mfma_f32_16x16x32_bf16 v[50:53], v[142:145], v[186:189], v[50:53]
	v_mfma_f32_16x16x32_bf16 v[42:45], v[150:153], v[186:189], v[42:45]
	v_mfma_f32_16x16x32_bf16 v[34:37], v[142:145], v[194:197], v[34:37]
	v_mfma_f32_16x16x32_bf16 v[26:29], v[150:153], v[194:197], v[26:29]
	v_mfma_f32_16x16x32_bf16 v[18:21], v[142:145], v[216:219], v[18:21]
	v_mfma_f32_16x16x32_bf16 v[10:13], v[150:153], v[216:219], v[10:13]
	v_mfma_f32_16x16x32_bf16 v[66:69], v[146:149], v[182:185], v[66:69]
	v_mfma_f32_16x16x32_bf16 v[58:61], v[154:157], v[182:185], v[58:61]
	v_mfma_f32_16x16x32_bf16 v[50:53], v[146:149], v[190:193], v[50:53]
	v_mfma_f32_16x16x32_bf16 v[42:45], v[154:157], v[190:193], v[42:45]
	v_mfma_f32_16x16x32_bf16 v[34:37], v[146:149], v[212:215], v[34:37]
	v_mfma_f32_16x16x32_bf16 v[26:29], v[154:157], v[212:215], v[26:29]
	v_mfma_f32_16x16x32_bf16 v[18:21], v[146:149], v[220:223], v[18:21]
	v_mfma_f32_16x16x32_bf16 v[10:13], v[154:157], v[220:223], v[10:13]
	v_mfma_f32_16x16x32_bf16 v[62:65], v[162:165], v[178:181], v[62:65]
	v_mfma_f32_16x16x32_bf16 v[54:57], v[170:173], v[178:181], v[54:57]
	v_mfma_f32_16x16x32_bf16 v[46:49], v[162:165], v[186:189], v[46:49]
	v_mfma_f32_16x16x32_bf16 v[38:41], v[170:173], v[186:189], v[38:41]
	v_mfma_f32_16x16x32_bf16 v[30:33], v[162:165], v[194:197], v[30:33]
	v_mfma_f32_16x16x32_bf16 v[22:25], v[170:173], v[194:197], v[22:25]
	v_mfma_f32_16x16x32_bf16 v[14:17], v[162:165], v[216:219], v[14:17]
	v_mfma_f32_16x16x32_bf16 v[6:9], v[170:173], v[216:219], v[6:9]
	v_mfma_f32_16x16x32_bf16 v[62:65], v[166:169], v[182:185], v[62:65]
	v_mfma_f32_16x16x32_bf16 v[54:57], v[174:177], v[182:185], v[54:57]
	v_mfma_f32_16x16x32_bf16 v[46:49], v[166:169], v[190:193], v[46:49]
	v_mfma_f32_16x16x32_bf16 v[38:41], v[174:177], v[190:193], v[38:41]
	v_mfma_f32_16x16x32_bf16 v[30:33], v[166:169], v[212:215], v[30:33]
	v_mfma_f32_16x16x32_bf16 v[22:25], v[174:177], v[212:215], v[22:25]
	v_mfma_f32_16x16x32_bf16 v[14:17], v[166:169], v[220:223], v[14:17]
	v_mfma_f32_16x16x32_bf16 v[6:9], v[174:177], v[220:223], v[6:9]
	s_barrier
	s_add_i32 s59, s59, 2
	s_add_u32 s26, s26, 0x100
	s_addc_u32 s27, s27, 0
	s_add_u32 s57, s57, 0x100
	s_addc_u32 s58, s58, 0
	s_cmp_gt_u32 s59, 29
	s_cbranch_scc0 .LBB0_137
	s_and_b64 vcc, exec, s[16:17]
	s_cbranch_vccz .LBB0_140
	s_barrier

; #define PG8_STAGE(bufoff, gbase, voff) do { _Pragma("unroll") for (int _i = 0; _i < 2; ++_i) \
;         __builtin_amdgcn_global_load_lds((const unsigned*)((const char*)(gbase) + (voff)[_i]), (LAS unsigned*)(lds + (bufoff) + ldsw + _i * 8192), 16, 0, 0); } while (0)
; #define PG8_WAIT_V(n) asm volatile("s_waitcnt vmcnt(" #n ")" ::: "memory")
; #define PG8_BAR __builtin_amdgcn_s_barrier()
; template <class Epi, class Sched>
; __device__ __forceinline__ void gemm_phase(LAS unsigned char* lds, const Gemm g, const Sched& S, const Epi& E) {
;     ...
;     for (int i = 0; i < 2; ++i) { int R, C; stage_rc(tid * 16 + i * 8192, R, C); const int Rb = Epi::PERM ? ((R & ~31) + perm32(R & 31)) : R;
;         voffA[i] = (unsigned)(R * g.lda + C) * 2u; voffB[i] = (unsigned)(Rb * g.ldb + C) * 2u; }
;     const size_t kstep = (size_t)(BK * 2);
;     const size_t hstepA = (size_t)HALF * g.lda * 2, hstepB = (size_t)HALF * g.ldb * 2;
;     const size_t tstepA = 2 * hstepA, tstepB = 2 * hstepB;
;     const unsigned ldsw = (unsigned)wid * 1024u;
;     const int aoff = lds_byte(wr * 64 + fr, fq * 8), boff = lds_byte(wc * 32 + fr, fq * 8);
;     ...
;     Unit cur, nxt; int ui = 0;
;     if (!S.next(0, cur)) return;
;     f32x4 acc[2][2][4][2];
; #pragma unroll
;     for (int a = 0; a < 2; ++a)
; #pragma unroll
;         for (int b = 0; b < 2; ++b)
; #pragma unroll
;             for (int m = 0; m < 4; ++m)
; #pragma unroll
;                 for (int n = 0; n < 2; ++n) acc[a][b][m][n] = (f32x4){0.f, 0.f, 0.f, 0.f};
;     bf16x8 At[4][2], B0[2][2], B1[2][2];
;     const char* cA = (const char*)g.A + (size_t)cur.pm * tstepA + (size_t)cur.ka * 2; const char* cB = (const char*)g.Bt + (size_t)cur.pn * tstepB;
;     S.a_ready(cur);
;     PG8_STAGE(PG8_SB(0, 0), cB, voffB); PG8_STAGE(PG8_SB(0, 1), cB + hstepB, voffB); PG8_STAGE(PG8_SA(0, 0), cA, voffA); PG8_STAGE(PG8_SA(0, 1), cA + hstepA, voffA);
;     if (wr == 1) PG8_BAR;
;     PG8_WAIT_V(2); PG8_BAR;
;     PG8_STAGE(PG8_SB(1, 0), cB + kstep, voffB); PG8_STAGE(PG8_SA(1, 0), cA + kstep, voffA); PG8_STAGE(PG8_SB(1, 1), cB + hstepB + kstep, voffB);
;     PG8_WAIT_V(6); PG8_BAR;
.LBB0_267:
	v_lshl_add_u64 v[14:15], s[24:25], 0, v[4:5]
	v_mov_b32_e32 v3, v5
	v_and_b32_e32 v142, 15, v143
	v_and_b32_e32 v22, 48, v143
	v_lshlrev_b32_e32 v23, 2, v143
	v_lshl_add_u64 v[16:17], s[24:25], 0, v[2:3]
	s_and_b32 s48, s44, 3
	v_lshl_or_b32 v22, v142, 6, v22
	s_lshl_b32 s4, s47, 13
	v_and_b32_e32 v23, 32, v23
	s_add_i32 m0, s50, 0x18000
	v_lshl_add_u64 v[14:15], v[14:15], 0, s[36:37]
	v_lshl_add_u64 v[18:19], s[20:21], 0, v[4:5]
	v_bitop3_b32 v24, v22, s4, v23 bitop3:0xde
	s_lshl_b32 s4, s48, 12
	s_waitcnt vmcnt(2)
	s_barrier
	global_load_lds_dwordx4 v[14:15], off
	v_lshl_add_u64 v[14:15], v[16:17], 0, s[36:37]
	s_add_i32 m0, s50, 0x1a000
	s_add_i32 s54, s50, 0x8000
	s_add_i32 s55, s50, 0xa000
	v_lshl_add_u64 v[20:21], s[20:21], 0, v[2:3]
	v_bitop3_b32 v144, v22, s4, v23 bitop3:0xde
	global_load_lds_dwordx4 v[14:15], off
	v_lshl_add_u64 v[14:15], v[18:19], 0, s[36:37]
	s_mov_b32 m0, s54
	s_add_u32 s4, s24, 0x158080
	global_load_lds_dwordx4 v[14:15], off
	v_lshl_add_u64 v[14:15], v[20:21], 0, s[36:37]
	s_mov_b32 m0, s55
	s_addc_u32 s5, s25, 0
	global_load_lds_dwordx4 v[14:15], off
	s_add_i32 m0, s50, 0x1c000
	v_lshl_add_u64 v[14:15], s[4:5], 0, v[4:5]
	global_load_lds_dwordx4 v[14:15], off
	v_lshl_add_u64 v[14:15], s[4:5], 0, v[2:3]
	s_add_i32 m0, s50, 0x1e000
	s_movk_i32 s10, 0x1580
	global_load_lds_dwordx4 v[14:15], off
	v_lshrrev_b32_e32 v11, 1, v11
	v_mul_lo_u32 v10, v10, s10
	s_mov_b32 s22, 0x15800
	v_mad_u64_u32 v[10:11], s[4:5], v11, s22, v[10:11]
	v_or_b32_e32 v10, v10, v12
	v_add_lshl_u32 v134, v10, v13, 1
	v_lshrrev_b32_e32 v10, 1, v6
	v_mul_lo_u32 v6, v7, s10
	v_mad_u64_u32 v[6:7], s[4:5], v10, s22, v[6:7]
	s_waitcnt vmcnt(6)
	v_or_b32_e32 v6, v6, v8
	s_cmpk_lt_u32 s45, 0x100
	v_add_lshl_u32 v136, v6, v9, 1
	v_mov_b32_e32 v6, 0
	v_readlane_b32 s4, v254, 13
	s_cselect_b64 s[18:19], -1, 0
	v_mov_b32_e32 v135, v5
	v_mov_b32_e32 v137, v5
	s_mov_b32 s59, 0
	v_add_u32_e32 v145, 0, v24
	s_mov_b32 s10, s4
	v_readlane_b32 s46, v253, 61
	v_mov_b32_e32 v7, v6
	v_mov_b32_e32 v8, v6
	v_mov_b32_e32 v9, v6
	v_mov_b32_e32 v10, v6
	v_mov_b32_e32 v11, v6
	v_mov_b32_e32 v12, v6
	v_mov_b32_e32 v13, v6
	v_mov_b32_e32 v14, v6
	v_mov_b32_e32 v15, v6
	v_mov_b32_e32 v16, v6
	v_mov_b32_e32 v17, v6
	v_mov_b32_e32 v18, v6
	v_mov_b32_e32 v19, v6
	v_mov_b32_e32 v20, v6
	v_mov_b32_e32 v21, v6
	v_mov_b32_e32 v22, v6
	v_mov_b32_e32 v23, v6
	v_mov_b32_e32 v24, v6
	v_mov_b32_e32 v25, v6
	v_mov_b32_e32 v30, v6
	v_mov_b32_e32 v31, v6
	v_mov_b32_e32 v32, v6
	v_mov_b32_e32 v33, v6
	v_mov_b32_e32 v38, v6
	v_mov_b32_e32 v39, v6
	v_mov_b32_e32 v40, v6
	v_mov_b32_e32 v41, v6
	v_mov_b32_e32 v46, v6
	v_mov_b32_e32 v47, v6
	v_mov_b32_e32 v48, v6
	v_mov_b32_e32 v49, v6
	v_mov_b32_e32 v26, v6
	v_mov_b32_e32 v27, v6
	v_mov_b32_e32 v28, v6
	v_mov_b32_e32 v29, v6
	v_mov_b32_e32 v34, v6
	v_mov_b32_e32 v35, v6
	v_mov_b32_e32 v36, v6
	v_mov_b32_e32 v37, v6
	v_mov_b32_e32 v42, v6
	v_mov_b32_e32 v43, v6
	v_mov_b32_e32 v44, v6
	v_mov_b32_e32 v45, v6
	v_mov_b32_e32 v50, v6
	v_mov_b32_e32 v51, v6
	v_mov_b32_e32 v52, v6
	v_mov_b32_e32 v53, v6
	v_mov_b32_e32 v54, v6
	v_mov_b32_e32 v55, v6
	v_mov_b32_e32 v56, v6
	v_mov_b32_e32 v57, v6
	v_mov_b32_e32 v58, v6
	v_mov_b32_e32 v59, v6
	v_mov_b32_e32 v60, v6
	v_mov_b32_e32 v61, v6
	v_mov_b32_e32 v62, v6
	v_mov_b32_e32 v63, v6
	v_mov_b32_e32 v64, v6
	v_mov_b32_e32 v65, v6
	v_mov_b32_e32 v66, v6
	v_mov_b32_e32 v67, v6
	v_mov_b32_e32 v68, v6
	v_mov_b32_e32 v69, v6
	v_mov_b32_e32 v70, v6
	v_mov_b32_e32 v71, v6
	v_mov_b32_e32 v72, v6
	v_mov_b32_e32 v73, v6
	v_mov_b32_e32 v74, v6
	v_mov_b32_e32 v75, v6
	v_mov_b32_e32 v76, v6
	v_mov_b32_e32 v77, v6
	v_mov_b32_e32 v78, v6
	v_mov_b32_e32 v79, v6
	v_mov_b32_e32 v80, v6
	v_mov_b32_e32 v81, v6
	v_mov_b32_e32 v82, v6
	v_mov_b32_e32 v83, v6
	v_mov_b32_e32 v84, v6
	v_mov_b32_e32 v85, v6
	v_mov_b32_e32 v86, v6
	v_mov_b32_e32 v87, v6
	v_mov_b32_e32 v88, v6
	v_mov_b32_e32 v89, v6
	v_mov_b32_e32 v94, v6
	v_mov_b32_e32 v95, v6
	v_mov_b32_e32 v96, v6
	v_mov_b32_e32 v97, v6
	v_mov_b32_e32 v102, v6
	v_mov_b32_e32 v103, v6
	v_mov_b32_e32 v104, v6
	v_mov_b32_e32 v105, v6
	v_mov_b32_e32 v114, v6
	v_mov_b32_e32 v115, v6
	v_mov_b32_e32 v116, v6
	v_mov_b32_e32 v117, v6
	v_mov_b32_e32 v90, v6
	v_mov_b32_e32 v91, v6
	v_mov_b32_e32 v92, v6
	v_mov_b32_e32 v93, v6
	v_mov_b32_e32 v98, v6
	v_mov_b32_e32 v99, v6
	v_mov_b32_e32 v100, v6
	v_mov_b32_e32 v101, v6
	v_mov_b32_e32 v106, v6
	v_mov_b32_e32 v107, v6
	v_mov_b32_e32 v108, v6
	v_mov_b32_e32 v109, v6
	v_mov_b32_e32 v110, v6
	v_mov_b32_e32 v111, v6
	v_mov_b32_e32 v112, v6
	v_mov_b32_e32 v113, v6
	v_mov_b32_e32 v118, v6
	v_mov_b32_e32 v119, v6
	v_mov_b32_e32 v120, v6
	v_mov_b32_e32 v121, v6
	v_mov_b32_e32 v122, v6
	v_mov_b32_e32 v123, v6
	v_mov_b32_e32 v124, v6
	v_mov_b32_e32 v125, v6
	v_mov_b32_e32 v126, v6
	v_mov_b32_e32 v127, v6
	v_mov_b32_e32 v128, v6
	v_mov_b32_e32 v129, v6
	v_mov_b32_e32 v130, v6
	v_mov_b32_e32 v131, v6
	v_mov_b32_e32 v132, v6
	v_mov_b32_e32 v133, v6
	s_barrier
	s_branch .LBB0_270
	s_nop 0
	s_nop 0
	s_nop 0
	s_nop 0
	s_nop 0
	s_nop 0
	s_nop 0
	s_nop 0
	s_nop 0
	s_nop 0
	s_nop 0
	s_nop 0
	s_nop 0
	s_nop 0
	s_nop 0
	s_nop 0
	s_nop 0
	s_nop 0
	s_nop 0
	s_nop 0
	s_nop 0
	s_nop 0
	s_nop 0
	s_nop 0
	s_nop 0
	s_nop 0
	s_nop 0
	s_nop 0
	s_nop 0
	s_nop 0
	s_nop 0
	s_nop 0
	s_nop 0
	s_nop 0
	s_nop 0
	s_nop 0
	s_nop 0
	s_nop 0
	s_nop 0
	s_nop 0
	s_nop 0
	s_nop 0
	s_nop 0
	s_nop 0
	s_nop 0
	s_nop 0
	s_nop 0
	s_nop 0
	s_nop 0
	s_nop 0
	s_nop 0
	s_nop 0
	s_nop 0
	s_nop 0

; #define PG8_STAGE(bufoff, gbase, voff) do { _Pragma("unroll") for (int _i = 0; _i < 2; ++_i) \
;         __builtin_amdgcn_global_load_lds((const unsigned*)((const char*)(gbase) + (voff)[_i]), (LAS unsigned*)(lds + (bufoff) + ldsw + _i * 8192), 16, 0, 0); } while (0)
; #define PG8_LDA(dst, b, h) do { _Pragma("unroll") for (int m = 0; m < 4; ++m) _Pragma("unroll") for (int k = 0; k < 2; ++k) dst[m][k] = *(const LAS bf16x8*)(lds + PG8_SA(b, h) + aoff + m * 2048 + k * 1024); } while (0)
; #define PG8_LDB(dst, b, h) do { _Pragma("unroll") for (int n = 0; n < 2; ++n) _Pragma("unroll") for (int k = 0; k < 2; ++k) dst[n][k] = *(const LAS bf16x8*)(lds + PG8_SB(b, h) + boff + n * 2048 + k * 1024); } while (0)
; #define PG8_MMA(ai, bj, At, Bt) do { __builtin_amdgcn_s_setprio(1); _Pragma("unroll") for (int m = 0; m < 4; ++m) _Pragma("unroll") for (int n = 0; n < 2; ++n) _Pragma("unroll") for (int k = 0; k < 2; ++k) \
;         acc[ai][bj][m][n] = __builtin_amdgcn_mfma_f32_16x16x32_bf16(Bt[n][k], At[m][k], acc[ai][bj][m][n], 0, 0, 0); __builtin_amdgcn_s_setprio(0); } while (0)
; #define PG8_WAIT_V(n) asm volatile("s_waitcnt vmcnt(" #n ")" ::: "memory")
; #define PG8_WAIT_L(n) asm volatile("s_waitcnt lgkmcnt(" #n ")" ::: "memory")
; #define PG8_BAR __builtin_amdgcn_s_barrier()
; template <class Epi, class Sched>
; __device__ __forceinline__ void gemm_phase(LAS unsigned char* lds, const Gemm g, const Sched& S, const Epi& E) {
;     ...
;         for (int t = 0; t < nt; t += 2) {
;             const bool last = (t == nt - 2);
;             const char* a1 = cA + (size_t)(t + 1) * kstep;
;             const char* a2 = last ? nA : cA + (size_t)(t + 2) * kstep; const char* b2 = last ? nB : cB + (size_t)(t + 2) * kstep;
;             const char* a3 = a2 + kstep; const char* b3 = b2 + kstep;
;             if (last && has_next) S.a_ready(nxt);
;             PG8_LDB(B0, 0, 0); PG8_LDB(B1, 0, 1); PG8_SCHED; PG8_LDA(At, 0, 0); PG8_STAGE(PG8_SA(1, 1), a1 + hstepA, voffA);
;             PG8_WAIT_V(8); PG8_WAIT_L(0); PG8_BAR; PG8_MMA(0, 0, At, B0); PG8_MMA(0, 1, At, B1); PG8_BAR; PG8_SCHED;
;             PG8_LDA(At, 0, 1); PG8_STAGE(PG8_SB(0, 0), b2, voffB); PG8_STAGE(PG8_SB(0, 1), b2 + hstepB, voffB); PG8_STAGE(PG8_SA(0, 0), a2, voffA);
;             PG8_WAIT_V(8); PG8_WAIT_L(0); PG8_BAR; PG8_MMA(1, 0, At, B0); PG8_MMA(1, 1, At, B1); PG8_BAR; PG8_SCHED;
.LBB0_281:
	s_add_u32 s26, s20, s24
	s_addc_u32 s27, s21, s25
	s_add_u32 s26, s26, 0x100
	s_addc_u32 s27, s27, 0
	s_add_u32 s63, s60, s24
	s_addc_u32 s65, s61, s25
	s_add_i32 s67, 0, 0x10000
	s_cmpk_eq_i32 s24, 0x2a00
	s_cselect_b32 s29, s5, s27
	s_cselect_b32 s28, s4, s26
	s_cselect_b32 s27, s23, s65
	s_cselect_b32 s26, s22, s63
	s_add_i32 s63, 0, 0x14000
	v_add_u32_e32 v158, s67, v144
	v_add_u32_e32 v174, s63, v144
	ds_read_b128 v[146:149], v158
	ds_read_b128 v[150:153], v158 offset:1024
	ds_read_b128 v[154:157], v158 offset:2048
	ds_read_b128 v[158:161], v158 offset:3072
	ds_read_b128 v[162:165], v174
	ds_read_b128 v[166:169], v174 offset:1024
	ds_read_b128 v[170:173], v174 offset:2048
	ds_read_b128 v[174:177], v174 offset:3072
	v_lshl_add_u64 v[224:225], v[138:139], 0, s[24:25]
	s_add_i32 m0, s50, 0xc000
	ds_read_b128 v[178:181], v145
	ds_read_b128 v[182:185], v145 offset:1024
	ds_read_b128 v[186:189], v145 offset:2048
	ds_read_b128 v[190:193], v145 offset:3072
	ds_read_b128 v[194:197], v145 offset:4096
	ds_read_b128 v[212:215], v145 offset:5120
	ds_read_b128 v[216:219], v145 offset:6144
	ds_read_b128 v[220:223], v145 offset:7168
	global_load_lds_dwordx4 v[224:225], off
	v_lshl_add_u64 v[224:225], v[140:141], 0, s[24:25]
	s_add_i32 m0, s50, 0xe000
	s_nop 0
	global_load_lds_dwordx4 v[224:225], off
	s_waitcnt vmcnt(8)
	s_waitcnt lgkmcnt(0)
	s_barrier
	s_waitcnt lgkmcnt(0)
	v_mfma_f32_16x16x32_bf16 v[130:133], v[146:149], v[178:181], v[130:133]
	v_mfma_f32_16x16x32_bf16 v[126:129], v[154:157], v[178:181], v[126:129]
	v_mfma_f32_16x16x32_bf16 v[122:125], v[146:149], v[186:189], v[122:125]
	v_mfma_f32_16x16x32_bf16 v[118:121], v[154:157], v[186:189], v[118:121]
	v_mfma_f32_16x16x32_bf16 v[110:113], v[146:149], v[194:197], v[110:113]
	v_mfma_f32_16x16x32_bf16 v[106:109], v[154:157], v[194:197], v[106:109]
	v_mfma_f32_16x16x32_bf16 v[98:101], v[146:149], v[216:219], v[98:101]
	v_mfma_f32_16x16x32_bf16 v[90:93], v[154:157], v[216:219], v[90:93]
	v_mfma_f32_16x16x32_bf16 v[130:133], v[150:153], v[182:185], v[130:133]
	v_mfma_f32_16x16x32_bf16 v[126:129], v[158:161], v[182:185], v[126:129]
	v_mfma_f32_16x16x32_bf16 v[122:125], v[150:153], v[190:193], v[122:125]
	v_mfma_f32_16x16x32_bf16 v[118:121], v[158:161], v[190:193], v[118:121]
	v_mfma_f32_16x16x32_bf16 v[110:113], v[150:153], v[212:215], v[110:113]
	v_mfma_f32_16x16x32_bf16 v[106:109], v[158:161], v[212:215], v[106:109]
	v_mfma_f32_16x16x32_bf16 v[98:101], v[150:153], v[220:223], v[98:101]
	v_mfma_f32_16x16x32_bf16 v[90:93], v[158:161], v[220:223], v[90:93]
	v_mfma_f32_16x16x32_bf16 v[114:117], v[162:165], v[178:181], v[114:117]
	v_mfma_f32_16x16x32_bf16 v[102:105], v[170:173], v[178:181], v[102:105]
	v_mfma_f32_16x16x32_bf16 v[94:97], v[162:165], v[186:189], v[94:97]
	v_mfma_f32_16x16x32_bf16 v[86:89], v[170:173], v[186:189], v[86:89]
	v_mfma_f32_16x16x32_bf16 v[82:85], v[162:165], v[194:197], v[82:85]
	v_mfma_f32_16x16x32_bf16 v[78:81], v[170:173], v[194:197], v[78:81]
	v_mfma_f32_16x16x32_bf16 v[74:77], v[162:165], v[216:219], v[74:77]
	v_mfma_f32_16x16x32_bf16 v[70:73], v[170:173], v[216:219], v[70:73]
	v_mfma_f32_16x16x32_bf16 v[114:117], v[166:169], v[182:185], v[114:117]
	v_mfma_f32_16x16x32_bf16 v[102:105], v[174:177], v[182:185], v[102:105]
	v_mfma_f32_16x16x32_bf16 v[94:97], v[166:169], v[190:193], v[94:97]
	v_mfma_f32_16x16x32_bf16 v[86:89], v[174:177], v[190:193], v[86:89]
	v_mfma_f32_16x16x32_bf16 v[82:85], v[166:169], v[212:215], v[82:85]
	v_mfma_f32_16x16x32_bf16 v[78:81], v[174:177], v[212:215], v[78:81]
	v_mfma_f32_16x16x32_bf16 v[74:77], v[166:169], v[220:223], v[74:77]
	v_mfma_f32_16x16x32_bf16 v[70:73], v[174:177], v[220:223], v[70:73]
	s_barrier
	s_add_i32 s65, s67, s11
	v_lshl_add_u64 v[224:225], s[26:27], 0, v[4:5]
	s_mov_b32 m0, s65
	ds_read_b128 v[178:181], v145 offset:16384
	ds_read_b128 v[182:185], v145 offset:17408
	ds_read_b128 v[186:189], v145 offset:18432
	ds_read_b128 v[190:193], v145 offset:19456
	ds_read_b128 v[194:197], v145 offset:20480
	ds_read_b128 v[212:215], v145 offset:21504
	ds_read_b128 v[216:219], v145 offset:22528
	ds_read_b128 v[220:223], v145 offset:23552
	global_load_lds_dwordx4 v[224:225], off
	s_add_i32 m0, s65, 0x2000
	s_add_u32 s68, s26, 0x158000
	v_lshl_add_u64 v[226:227], s[26:27], 0, v[2:3]
	s_addc_u32 s69, s27, 0
	s_add_i32 s63, s63, s11
	global_load_lds_dwordx4 v[226:227], off
	s_mov_b32 m0, s63
	v_lshl_add_u64 v[230:231], s[28:29], 0, v[2:3]
	global_load_lds_dwordx4 v4, s[68:69]
	s_add_i32 m0, s63, 0x2000
	s_nop 0
	global_load_lds_dwordx4 v2, s[68:69]
	v_lshl_add_u64 v[228:229], s[28:29], 0, v[4:5]
	s_mov_b32 m0, s50
	s_nop 0
	global_load_lds_dwordx4 v[228:229], off
	s_mov_b32 m0, s51
	s_nop 0
	global_load_lds_dwordx4 v[230:231], off
	s_waitcnt vmcnt(8)
	s_waitcnt lgkmcnt(0)
	s_barrier
; #define PG8_STAGE(bufoff, gbase, voff) do { _Pragma("unroll") for (int _i = 0; _i < 2; ++_i) \
;         __builtin_amdgcn_global_load_lds((const unsigned*)((const char*)(gbase) + (voff)[_i]), (LAS unsigned*)(lds + (bufoff) + ldsw + _i * 8192), 16, 0, 0); } while (0)
; #define PG8_LDA(dst, b, h) do { _Pragma("unroll") for (int m = 0; m < 4; ++m) _Pragma("unroll") for (int k = 0; k < 2; ++k) dst[m][k] = *(const LAS bf16x8*)(lds + PG8_SA(b, h) + aoff + m * 2048 + k * 1024); } while (0)
; #define PG8_LDB(dst, b, h) do { _Pragma("unroll") for (int n = 0; n < 2; ++n) _Pragma("unroll") for (int k = 0; k < 2; ++k) dst[n][k] = *(const LAS bf16x8*)(lds + PG8_SB(b, h) + boff + n * 2048 + k * 1024); } while (0)
; #define PG8_MMA(ai, bj, At, Bt) do { __builtin_amdgcn_s_setprio(1); _Pragma("unroll") for (int m = 0; m < 4; ++m) _Pragma("unroll") for (int n = 0; n < 2; ++n) _Pragma("unroll") for (int k = 0; k < 2; ++k) \
;         acc[ai][bj][m][n] = __builtin_amdgcn_mfma_f32_16x16x32_bf16(Bt[n][k], At[m][k], acc[ai][bj][m][n], 0, 0, 0); __builtin_amdgcn_s_setprio(0); } while (0)
; #define PG8_WAIT_V(n) asm volatile("s_waitcnt vmcnt(" #n ")" ::: "memory")
; #define PG8_WAIT_L(n) asm volatile("s_waitcnt lgkmcnt(" #n ")" ::: "memory")
; #define PG8_BAR __builtin_amdgcn_s_barrier()
; #define PG8_SCHED __builtin_amdgcn_sched_barrier(0)
; template <class Epi, class Sched>
; __device__ __forceinline__ void gemm_phase(LAS unsigned char* lds, const Gemm g, const Sched& S, const Epi& E) {
;     ...
;             PG8_WAIT_V(8); PG8_WAIT_L(0); PG8_BAR; PG8_MMA(1, 0, At, B0); PG8_MMA(1, 1, At, B1); PG8_BAR; PG8_SCHED;
;             PG8_LDB(B0, 1, 0); PG8_LDB(B1, 1, 1); PG8_SCHED; PG8_LDA(At, 1, 0); PG8_STAGE(PG8_SA(0, 1), a2 + hstepA, voffA);
;             PG8_WAIT_V(8); PG8_WAIT_L(0); PG8_BAR; PG8_MMA(0, 0, At, B0); PG8_MMA(0, 1, At, B1); PG8_BAR; PG8_SCHED;
	s_waitcnt lgkmcnt(0)
	v_mfma_f32_16x16x32_bf16 v[66:69], v[146:149], v[178:181], v[66:69]
	v_mfma_f32_16x16x32_bf16 v[62:65], v[154:157], v[178:181], v[62:65]
	v_mfma_f32_16x16x32_bf16 v[58:61], v[146:149], v[186:189], v[58:61]
	v_mfma_f32_16x16x32_bf16 v[54:57], v[154:157], v[186:189], v[54:57]
	v_mfma_f32_16x16x32_bf16 v[50:53], v[146:149], v[194:197], v[50:53]
	v_mfma_f32_16x16x32_bf16 v[42:45], v[154:157], v[194:197], v[42:45]
	v_mfma_f32_16x16x32_bf16 v[34:37], v[146:149], v[216:219], v[34:37]
	v_mfma_f32_16x16x32_bf16 v[26:29], v[154:157], v[216:219], v[26:29]
	v_mfma_f32_16x16x32_bf16 v[66:69], v[150:153], v[182:185], v[66:69]
	v_mfma_f32_16x16x32_bf16 v[62:65], v[158:161], v[182:185], v[62:65]
	v_mfma_f32_16x16x32_bf16 v[58:61], v[150:153], v[190:193], v[58:61]
	v_mfma_f32_16x16x32_bf16 v[54:57], v[158:161], v[190:193], v[54:57]
	v_mfma_f32_16x16x32_bf16 v[50:53], v[150:153], v[212:215], v[50:53]
	v_mfma_f32_16x16x32_bf16 v[42:45], v[158:161], v[212:215], v[42:45]
	v_mfma_f32_16x16x32_bf16 v[34:37], v[150:153], v[220:223], v[34:37]
	v_mfma_f32_16x16x32_bf16 v[26:29], v[158:161], v[220:223], v[26:29]
	v_mfma_f32_16x16x32_bf16 v[46:49], v[162:165], v[178:181], v[46:49]
	v_mfma_f32_16x16x32_bf16 v[38:41], v[170:173], v[178:181], v[38:41]
	v_mfma_f32_16x16x32_bf16 v[30:33], v[162:165], v[186:189], v[30:33]
	v_mfma_f32_16x16x32_bf16 v[22:25], v[170:173], v[186:189], v[22:25]
	v_mfma_f32_16x16x32_bf16 v[18:21], v[162:165], v[194:197], v[18:21]
	v_mfma_f32_16x16x32_bf16 v[14:17], v[170:173], v[194:197], v[14:17]
	v_mfma_f32_16x16x32_bf16 v[10:13], v[162:165], v[216:219], v[10:13]
	v_mfma_f32_16x16x32_bf16 v[6:9], v[170:173], v[216:219], v[6:9]
	v_mfma_f32_16x16x32_bf16 v[46:49], v[166:169], v[182:185], v[46:49]
	v_mfma_f32_16x16x32_bf16 v[38:41], v[174:177], v[182:185], v[38:41]
	v_mfma_f32_16x16x32_bf16 v[30:33], v[166:169], v[190:193], v[30:33]
	v_mfma_f32_16x16x32_bf16 v[22:25], v[174:177], v[190:193], v[22:25]
	v_mfma_f32_16x16x32_bf16 v[18:21], v[166:169], v[212:215], v[18:21]
	v_mfma_f32_16x16x32_bf16 v[14:17], v[174:177], v[212:215], v[14:17]
	v_mfma_f32_16x16x32_bf16 v[10:13], v[166:169], v[220:223], v[10:13]
	v_mfma_f32_16x16x32_bf16 v[6:9], v[174:177], v[220:223], v[6:9]
	s_barrier
	s_add_i32 s63, 0, 0x18000
	s_add_i32 s65, 0, 0x1c000
	v_add_u32_e32 v158, s63, v144
	v_add_u32_e32 v174, s65, v144
	ds_read_b128 v[146:149], v158
	ds_read_b128 v[150:153], v158 offset:1024
	ds_read_b128 v[154:157], v158 offset:2048
	ds_read_b128 v[158:161], v158 offset:3072
	ds_read_b128 v[162:165], v174
	ds_read_b128 v[166:169], v174 offset:1024
	ds_read_b128 v[170:173], v174 offset:2048
	ds_read_b128 v[174:177], v174 offset:3072
	s_add_u32 s28, s28, 0x158000
	s_addc_u32 s29, s29, 0
	s_mov_b32 m0, s52
	ds_read_b128 v[178:181], v145 offset:32768
	ds_read_b128 v[182:185], v145 offset:33792
	ds_read_b128 v[186:189], v145 offset:34816
	ds_read_b128 v[190:193], v145 offset:35840
	ds_read_b128 v[194:197], v145 offset:36864
	ds_read_b128 v[212:215], v145 offset:37888
	ds_read_b128 v[216:219], v145 offset:38912
	ds_read_b128 v[220:223], v145 offset:39936
	global_load_lds_dwordx4 v4, s[28:29]
	s_mov_b32 m0, s53
	s_nop 0
	global_load_lds_dwordx4 v2, s[28:29]
	s_waitcnt vmcnt(8)
	s_waitcnt lgkmcnt(0)
	s_barrier
	s_waitcnt lgkmcnt(0)
	v_mfma_f32_16x16x32_bf16 v[130:133], v[146:149], v[178:181], v[130:133]
	v_mfma_f32_16x16x32_bf16 v[126:129], v[154:157], v[178:181], v[126:129]
	v_mfma_f32_16x16x32_bf16 v[122:125], v[146:149], v[186:189], v[122:125]
	v_mfma_f32_16x16x32_bf16 v[118:121], v[154:157], v[186:189], v[118:121]
	v_mfma_f32_16x16x32_bf16 v[110:113], v[146:149], v[194:197], v[110:113]
	v_mfma_f32_16x16x32_bf16 v[106:109], v[154:157], v[194:197], v[106:109]
	v_mfma_f32_16x16x32_bf16 v[98:101], v[146:149], v[216:219], v[98:101]
	v_mfma_f32_16x16x32_bf16 v[90:93], v[154:157], v[216:219], v[90:93]
	v_mfma_f32_16x16x32_bf16 v[130:133], v[150:153], v[182:185], v[130:133]
	v_mfma_f32_16x16x32_bf16 v[126:129], v[158:161], v[182:185], v[126:129]
	v_mfma_f32_16x16x32_bf16 v[122:125], v[150:153], v[190:193], v[122:125]
	v_mfma_f32_16x16x32_bf16 v[118:121], v[158:161], v[190:193], v[118:121]
	v_mfma_f32_16x16x32_bf16 v[110:113], v[150:153], v[212:215], v[110:113]
	v_mfma_f32_16x16x32_bf16 v[106:109], v[158:161], v[212:215], v[106:109]
	v_mfma_f32_16x16x32_bf16 v[98:101], v[150:153], v[220:223], v[98:101]
	v_mfma_f32_16x16x32_bf16 v[90:93], v[158:161], v[220:223], v[90:93]
	v_mfma_f32_16x16x32_bf16 v[114:117], v[162:165], v[178:181], v[114:117]
	v_mfma_f32_16x16x32_bf16 v[102:105], v[170:173], v[178:181], v[102:105]
	v_mfma_f32_16x16x32_bf16 v[94:97], v[162:165], v[186:189], v[94:97]
	v_mfma_f32_16x16x32_bf16 v[86:89], v[170:173], v[186:189], v[86:89]
	v_mfma_f32_16x16x32_bf16 v[82:85], v[162:165], v[194:197], v[82:85]
	v_mfma_f32_16x16x32_bf16 v[78:81], v[170:173], v[194:197], v[78:81]
	v_mfma_f32_16x16x32_bf16 v[74:77], v[162:165], v[216:219], v[74:77]
	v_mfma_f32_16x16x32_bf16 v[70:73], v[170:173], v[216:219], v[70:73]
	v_mfma_f32_16x16x32_bf16 v[114:117], v[166:169], v[182:185], v[114:117]
	v_mfma_f32_16x16x32_bf16 v[102:105], v[174:177], v[182:185], v[102:105]
	v_mfma_f32_16x16x32_bf16 v[94:97], v[166:169], v[190:193], v[94:97]
	v_mfma_f32_16x16x32_bf16 v[86:89], v[174:177], v[190:193], v[86:89]
	v_mfma_f32_16x16x32_bf16 v[82:85], v[166:169], v[212:215], v[82:85]
	v_mfma_f32_16x16x32_bf16 v[78:81], v[174:177], v[212:215], v[78:81]
	v_mfma_f32_16x16x32_bf16 v[74:77], v[166:169], v[220:223], v[74:77]
	v_mfma_f32_16x16x32_bf16 v[70:73], v[174:177], v[220:223], v[70:73]
	s_barrier
; #define PG8_STAGE(bufoff, gbase, voff) do { _Pragma("unroll") for (int _i = 0; _i < 2; ++_i) \
;         __builtin_amdgcn_global_load_lds((const unsigned*)((const char*)(gbase) + (voff)[_i]), (LAS unsigned*)(lds + (bufoff) + ldsw + _i * 8192), 16, 0, 0); } while (0)
; #define PG8_LDA(dst, b, h) do { _Pragma("unroll") for (int m = 0; m < 4; ++m) _Pragma("unroll") for (int k = 0; k < 2; ++k) dst[m][k] = *(const LAS bf16x8*)(lds + PG8_SA(b, h) + aoff + m * 2048 + k * 1024); } while (0)
; #define PG8_MMA(ai, bj, At, Bt) do { __builtin_amdgcn_s_setprio(1); _Pragma("unroll") for (int m = 0; m < 4; ++m) _Pragma("unroll") for (int n = 0; n < 2; ++n) _Pragma("unroll") for (int k = 0; k < 2; ++k) \
;         acc[ai][bj][m][n] = __builtin_amdgcn_mfma_f32_16x16x32_bf16(Bt[n][k], At[m][k], acc[ai][bj][m][n], 0, 0, 0); __builtin_amdgcn_s_setprio(0); } while (0)
; #define PG8_WAIT_V(n) asm volatile("s_waitcnt vmcnt(" #n ")" ::: "memory")
; #define PG8_WAIT_L(n) asm volatile("s_waitcnt lgkmcnt(" #n ")" ::: "memory")
; #define PG8_BAR __builtin_amdgcn_s_barrier()
; #define PG8_SCHED __builtin_amdgcn_sched_barrier(0)
; template <class Epi, class Sched>
; __device__ __forceinline__ void gemm_phase(LAS unsigned char* lds, const Gemm g, const Sched& S, const Epi& E) {
;     ...
;             PG8_LDA(At, 1, 1); PG8_STAGE(PG8_SB(1, 0), b3, voffB); PG8_STAGE(PG8_SB(1, 1), b3 + hstepB, voffB); PG8_STAGE(PG8_SA(1, 0), a3, voffA);
;             PG8_WAIT_V(8); PG8_WAIT_L(0); PG8_BAR; PG8_MMA(1, 0, At, B0); PG8_MMA(1, 1, At, B1); PG8_BAR; PG8_SCHED;
;         }
;         if (wr == 0) PG8_BAR;
	s_add_i32 s28, s63, s11
	v_lshl_add_u64 v[224:225], v[224:225], 0, s[36:37]
	s_mov_b32 m0, s28
	ds_read_b128 v[178:181], v145 offset:49152
	ds_read_b128 v[182:185], v145 offset:50176
	ds_read_b128 v[186:189], v145 offset:51200
	ds_read_b128 v[190:193], v145 offset:52224
	ds_read_b128 v[194:197], v145 offset:53248
	ds_read_b128 v[212:215], v145 offset:54272
	ds_read_b128 v[216:219], v145 offset:55296
	ds_read_b128 v[220:223], v145 offset:56320
	global_load_lds_dwordx4 v[224:225], off
	s_add_i32 m0, s28, 0x2000
	s_add_u32 s26, s26, 0x158080
	v_lshl_add_u64 v[224:225], v[226:227], 0, s[36:37]
	s_addc_u32 s27, s27, 0
	s_add_i32 s28, s65, s11
	global_load_lds_dwordx4 v[224:225], off
	s_mov_b32 m0, s28
	s_nop 0
	global_load_lds_dwordx4 v4, s[26:27]
	s_add_i32 m0, s28, 0x2000
	s_nop 0
	global_load_lds_dwordx4 v2, s[26:27]
	v_lshl_add_u64 v[224:225], v[228:229], 0, s[36:37]
	s_mov_b32 m0, s54
	s_nop 0
	global_load_lds_dwordx4 v[224:225], off
	v_lshl_add_u64 v[224:225], v[230:231], 0, s[36:37]
	s_mov_b32 m0, s55
	s_nop 0
	global_load_lds_dwordx4 v[224:225], off
	s_waitcnt vmcnt(8)
	s_waitcnt lgkmcnt(0)
	s_barrier
	s_waitcnt lgkmcnt(0)
	v_mfma_f32_16x16x32_bf16 v[66:69], v[146:149], v[178:181], v[66:69]
	v_mfma_f32_16x16x32_bf16 v[62:65], v[154:157], v[178:181], v[62:65]
	v_mfma_f32_16x16x32_bf16 v[58:61], v[146:149], v[186:189], v[58:61]
	v_mfma_f32_16x16x32_bf16 v[54:57], v[154:157], v[186:189], v[54:57]
	v_mfma_f32_16x16x32_bf16 v[50:53], v[146:149], v[194:197], v[50:53]
	v_mfma_f32_16x16x32_bf16 v[42:45], v[154:157], v[194:197], v[42:45]
	v_mfma_f32_16x16x32_bf16 v[34:37], v[146:149], v[216:219], v[34:37]
	v_mfma_f32_16x16x32_bf16 v[26:29], v[154:157], v[216:219], v[26:29]
	v_mfma_f32_16x16x32_bf16 v[66:69], v[150:153], v[182:185], v[66:69]
	v_mfma_f32_16x16x32_bf16 v[62:65], v[158:161], v[182:185], v[62:65]
	v_mfma_f32_16x16x32_bf16 v[58:61], v[150:153], v[190:193], v[58:61]
	v_mfma_f32_16x16x32_bf16 v[54:57], v[158:161], v[190:193], v[54:57]
	v_mfma_f32_16x16x32_bf16 v[50:53], v[150:153], v[212:215], v[50:53]
	v_mfma_f32_16x16x32_bf16 v[42:45], v[158:161], v[212:215], v[42:45]
	v_mfma_f32_16x16x32_bf16 v[34:37], v[150:153], v[220:223], v[34:37]
	v_mfma_f32_16x16x32_bf16 v[26:29], v[158:161], v[220:223], v[26:29]
	v_mfma_f32_16x16x32_bf16 v[46:49], v[162:165], v[178:181], v[46:49]
	v_mfma_f32_16x16x32_bf16 v[38:41], v[170:173], v[178:181], v[38:41]
	v_mfma_f32_16x16x32_bf16 v[30:33], v[162:165], v[186:189], v[30:33]
	v_mfma_f32_16x16x32_bf16 v[22:25], v[170:173], v[186:189], v[22:25]
	v_mfma_f32_16x16x32_bf16 v[18:21], v[162:165], v[194:197], v[18:21]
	v_mfma_f32_16x16x32_bf16 v[14:17], v[170:173], v[194:197], v[14:17]
	v_mfma_f32_16x16x32_bf16 v[10:13], v[162:165], v[216:219], v[10:13]
	v_mfma_f32_16x16x32_bf16 v[6:9], v[170:173], v[216:219], v[6:9]
	v_mfma_f32_16x16x32_bf16 v[46:49], v[166:169], v[182:185], v[46:49]
	v_mfma_f32_16x16x32_bf16 v[38:41], v[174:177], v[182:185], v[38:41]
	v_mfma_f32_16x16x32_bf16 v[30:33], v[166:169], v[190:193], v[30:33]
	v_mfma_f32_16x16x32_bf16 v[22:25], v[174:177], v[190:193], v[22:25]
	v_mfma_f32_16x16x32_bf16 v[18:21], v[166:169], v[212:215], v[18:21]
	v_mfma_f32_16x16x32_bf16 v[14:17], v[174:177], v[212:215], v[14:17]
	v_mfma_f32_16x16x32_bf16 v[10:13], v[166:169], v[220:223], v[10:13]
	v_mfma_f32_16x16x32_bf16 v[6:9], v[174:177], v[220:223], v[6:9]
	s_barrier
	s_add_i32 s62, s62, 2
	s_add_u32 s24, s24, 0x100
	s_addc_u32 s25, s25, 0
	s_cmpk_gt_u32 s62, 0x53
	s_cbranch_scc0 .LBB0_281
	s_and_b64 vcc, exec, s[18:19]
	s_cbranch_vccz .LBB0_284
	s_barrier

; #define PG8_STAGE(bufoff, gbase, voff) do { _Pragma("unroll") for (int _i = 0; _i < 2; ++_i) \
;         __builtin_amdgcn_global_load_lds((const unsigned*)((const char*)(gbase) + (voff)[_i]), (LAS unsigned*)(lds + (bufoff) + ldsw + _i * 8192), 16, 0, 0); } while (0)
; #define PG8_WAIT_V(n) asm volatile("s_waitcnt vmcnt(" #n ")" ::: "memory")
; #define PG8_BAR __builtin_amdgcn_s_barrier()
; template <class Epi, class Sched>
; __device__ __forceinline__ void gemm_phase(LAS unsigned char* lds, const Gemm g, const Sched& S, const Epi& E) {
;     ...
;     const int aoff = lds_byte(wr * 64 + fr, fq * 8), boff = lds_byte(wc * 32 + fr, fq * 8);
;     ...
;     Unit cur, nxt; int ui = 0;
;     if (!S.next(0, cur)) return;
;     f32x4 acc[2][2][4][2];
; #pragma unroll
;     for (int a = 0; a < 2; ++a)
; #pragma unroll
;         for (int b = 0; b < 2; ++b)
; #pragma unroll
;             for (int m = 0; m < 4; ++m)
; #pragma unroll
;                 for (int n = 0; n < 2; ++n) acc[a][b][m][n] = (f32x4){0.f, 0.f, 0.f, 0.f};
;     bf16x8 At[4][2], B0[2][2], B1[2][2];
;     const char* cA = (const char*)g.A + (size_t)cur.pm * tstepA + (size_t)cur.ka * 2; const char* cB = (const char*)g.Bt + (size_t)cur.pn * tstepB;
;     S.a_ready(cur);
;     PG8_STAGE(PG8_SB(0, 0), cB, voffB); PG8_STAGE(PG8_SB(0, 1), cB + hstepB, voffB); PG8_STAGE(PG8_SA(0, 0), cA, voffA); PG8_STAGE(PG8_SA(0, 1), cA + hstepA, voffA);
;     if (wr == 1) PG8_BAR;
;     PG8_WAIT_V(2); PG8_BAR;
;     PG8_STAGE(PG8_SB(1, 0), cB + kstep, voffB); PG8_STAGE(PG8_SA(1, 0), cA + kstep, voffA); PG8_STAGE(PG8_SB(1, 1), cB + hstepB + kstep, voffB);
;     PG8_WAIT_V(6); PG8_BAR;
.LBB0_507:
	v_lshrrev_b32_e32 v20, 1, v4
	v_and_b32_e32 v20, 24, v20
	v_and_b32_e32 v21, 15, v4
	v_lshlrev_b32_e32 v22, 1, v20
	v_lshlrev_b32_e32 v4, 2, v4
	s_and_b32 s20, s17, 3
	v_lshl_or_b32 v235, s18, 6, v21
	v_lshl_or_b32 v21, v21, 6, v22
	s_lshl_b32 s17, s18, 13
	v_and_b32_e32 v4, 32, v4
	s_add_i32 m0, s50, 0x18000
	v_lshl_add_u64 v[12:13], v[12:13], 0, s[36:37]
	v_bitop3_b32 v22, v21, s17, v4 bitop3:0xde
	s_lshl_b32 s17, s20, 12
	s_waitcnt vmcnt(2)
	s_barrier
	global_load_lds_dwordx4 v[12:13], off
	v_lshl_add_u64 v[10:11], v[10:11], 0, s[36:37]
	s_add_i32 m0, s50, 0x1a000
	s_add_i32 s54, s50, 0x8000
	s_add_i32 s55, s50, 0xa000
	global_load_lds_dwordx4 v[10:11], off
	v_lshl_add_u64 v[6:7], v[6:7], 0, s[36:37]
	s_mov_b32 m0, s54
	s_add_u32 s18, s42, 0x80080
	global_load_lds_dwordx4 v[6:7], off
	v_lshl_add_u64 v[6:7], v[8:9], 0, s[36:37]
	s_mov_b32 m0, s55
	s_addc_u32 s19, s43, 0
	global_load_lds_dwordx4 v[6:7], off
	s_add_i32 m0, s50, 0x1c000
	v_lshl_add_u64 v[6:7], s[18:19], 0, v[212:213]
	global_load_lds_dwordx4 v[6:7], off
	v_lshl_add_u64 v[6:7], s[18:19], 0, v[216:217]
	s_add_i32 m0, s50, 0x1e000
	v_bitop3_b32 v236, v21, s17, v4 bitop3:0xde
	global_load_lds_dwordx4 v[6:7], off
	v_lshlrev_b32_e32 v4, 2, v20
	v_lshl_add_u64 v[218:219], s[12:13], 0, v[4:5]
	v_lshl_add_u64 v[220:221], s[10:11], 0, v[4:5]
	v_lshl_add_u64 v[222:223], s[14:15], 0, v[4:5]
	v_lshlrev_b32_e32 v4, 15, v14
	v_and_b32_e32 v4, 0xffff0000, v4
	v_lshl_add_u32 v4, v15, 12, v4
	v_and_b32_e32 v6, 1, v14
	v_lshl_or_b32 v4, v6, 6, v4
	v_lshl_add_u32 v224, v16, 1, v4
	v_lshlrev_b32_e32 v4, 15, v17
	v_and_b32_e32 v4, 0xffff0000, v4
	s_waitcnt vmcnt(6)
	v_lshl_add_u32 v4, v18, 12, v4
	v_and_b32_e32 v6, 1, v17
	s_cmpk_lt_u32 s16, 0x100
	v_lshl_or_b32 v4, v6, 6, v4
	s_cselect_b64 s[16:17], -1, 0
	s_lshl_b32 s56, s20, 6
	v_mov_b32_e32 v225, v5
	v_lshl_add_u32 v226, v19, 1, v4
	v_mov_b32_e32 v227, v5
	s_mov_b32 s57, 0
	v_add_u32_e32 v237, 0, v22
	v_lshlrev_b32_e32 v4, 1, v20
	s_barrier
	s_branch .LBB0_510
	s_nop 0
	s_nop 0
	s_nop 0
	s_nop 0
	s_nop 0
	s_nop 0
	s_nop 0
	s_nop 0
	s_nop 0
	s_nop 0
	s_nop 0
	s_nop 0
	s_nop 0
	s_nop 0
	s_nop 0
	s_nop 0
	s_nop 0
	s_nop 0
	s_nop 0
	s_nop 0
	s_nop 0
	s_nop 0
	s_nop 0
.LBB0_508:
	s_mov_b64 s[26:27], 0

; #define PG8_STAGE(bufoff, gbase, voff) do { _Pragma("unroll") for (int _i = 0; _i < 2; ++_i) \
;         __builtin_amdgcn_global_load_lds((const unsigned*)((const char*)(gbase) + (voff)[_i]), (LAS unsigned*)(lds + (bufoff) + ldsw + _i * 8192), 16, 0, 0); } while (0)
; #define PG8_LDA(dst, b, h) do { _Pragma("unroll") for (int m = 0; m < 4; ++m) _Pragma("unroll") for (int k = 0; k < 2; ++k) dst[m][k] = *(const LAS bf16x8*)(lds + PG8_SA(b, h) + aoff + m * 2048 + k * 1024); } while (0)
; #define PG8_LDB(dst, b, h) do { _Pragma("unroll") for (int n = 0; n < 2; ++n) _Pragma("unroll") for (int k = 0; k < 2; ++k) dst[n][k] = *(const LAS bf16x8*)(lds + PG8_SB(b, h) + boff + n * 2048 + k * 1024); } while (0)
; #define PG8_MMA(ai, bj, At, Bt) do { __builtin_amdgcn_s_setprio(1); _Pragma("unroll") for (int m = 0; m < 4; ++m) _Pragma("unroll") for (int n = 0; n < 2; ++n) _Pragma("unroll") for (int k = 0; k < 2; ++k) \
;         acc[ai][bj][m][n] = __builtin_amdgcn_mfma_f32_16x16x32_bf16(Bt[n][k], At[m][k], acc[ai][bj][m][n], 0, 0, 0); __builtin_amdgcn_s_setprio(0); } while (0)
; #define PG8_WAIT_V(n) asm volatile("s_waitcnt vmcnt(" #n ")" ::: "memory")
; #define PG8_WAIT_L(n) asm volatile("s_waitcnt lgkmcnt(" #n ")" ::: "memory")
; #define PG8_BAR __builtin_amdgcn_s_barrier()
; template <class Epi, class Sched>
; __device__ __forceinline__ void gemm_phase(LAS unsigned char* lds, const Gemm g, const Sched& S, const Epi& E) {
;     ...
;         for (int t = 0; t < nt; t += 2) {
;             const bool last = (t == nt - 2);
;             const char* a1 = cA + (size_t)(t + 1) * kstep;
;             const char* a2 = last ? nA : cA + (size_t)(t + 2) * kstep; const char* b2 = last ? nB : cB + (size_t)(t + 2) * kstep;
;             const char* a3 = a2 + kstep; const char* b3 = b2 + kstep;
;             if (last && has_next) S.a_ready(nxt);
;             PG8_LDB(B0, 0, 0); PG8_LDB(B1, 0, 1); PG8_SCHED; PG8_LDA(At, 0, 0); PG8_STAGE(PG8_SA(1, 1), a1 + hstepA, voffA);
;             PG8_WAIT_V(8); PG8_WAIT_L(0); PG8_BAR; PG8_MMA(0, 0, At, B0); PG8_MMA(0, 1, At, B1); PG8_BAR; PG8_SCHED;
;             PG8_LDA(At, 0, 1); PG8_STAGE(PG8_SB(0, 0), b2, voffB); PG8_STAGE(PG8_SB(0, 1), b2 + hstepB, voffB); PG8_STAGE(PG8_SA(0, 0), a2, voffA);
;             PG8_WAIT_V(8); PG8_WAIT_L(0); PG8_BAR; PG8_MMA(1, 0, At, B0); PG8_MMA(1, 1, At, B1); PG8_BAR; PG8_SCHED;
.LBB0_513:
	s_add_u32 s42, s38, 0xfff80080
	s_addc_u32 s43, s39, -1
	s_add_i32 s61, 0, 0x10000
	s_cmp_eq_u32 s60, 28
	s_cselect_b32 s45, s21, s43
	s_cselect_b32 s44, s27, s42
	s_cselect_b32 s43, s19, s59
	s_cselect_b32 s42, s29, s58
	s_add_i32 s64, 0, 0x14000
	v_add_u32_e32 v98, s61, v236
	v_add_u32_e32 v162, s64, v236
	ds_read_b128 v[86:89], v98
	ds_read_b128 v[90:93], v98 offset:1024
	ds_read_b128 v[94:97], v98 offset:2048
	ds_read_b128 v[98:101], v98 offset:3072
	ds_read_b128 v[150:153], v162
	ds_read_b128 v[154:157], v162 offset:1024
	ds_read_b128 v[158:161], v162 offset:2048
	ds_read_b128 v[162:165], v162 offset:3072
	s_add_i32 m0, s50, 0xc000
	ds_read_b128 v[166:169], v237
	ds_read_b128 v[170:173], v237 offset:1024
	ds_read_b128 v[174:177], v237 offset:2048
	ds_read_b128 v[178:181], v237 offset:3072
	ds_read_b128 v[182:185], v237 offset:4096
	ds_read_b128 v[186:189], v237 offset:5120
	ds_read_b128 v[190:193], v237 offset:6144
	ds_read_b128 v[194:197], v237 offset:7168
	global_load_lds_dwordx4 v224, s[38:39]
	s_add_i32 m0, s50, 0xe000
	s_nop 0
	global_load_lds_dwordx4 v226, s[38:39]
	s_waitcnt vmcnt(8)
	s_waitcnt lgkmcnt(0)
	s_barrier
	s_waitcnt lgkmcnt(0)
	v_mfma_f32_16x16x32_bf16 v[146:149], v[86:89], v[166:169], v[146:149]
	v_mfma_f32_16x16x32_bf16 v[142:145], v[94:97], v[166:169], v[142:145]
	v_mfma_f32_16x16x32_bf16 v[130:133], v[86:89], v[174:177], v[130:133]
	v_mfma_f32_16x16x32_bf16 v[126:129], v[94:97], v[174:177], v[126:129]
	v_mfma_f32_16x16x32_bf16 v[114:117], v[86:89], v[182:185], v[114:117]
	v_mfma_f32_16x16x32_bf16 v[110:113], v[94:97], v[182:185], v[110:113]
	v_mfma_f32_16x16x32_bf16 v[82:85], v[86:89], v[190:193], v[82:85]
	v_mfma_f32_16x16x32_bf16 v[78:81], v[94:97], v[190:193], v[78:81]
	v_mfma_f32_16x16x32_bf16 v[146:149], v[90:93], v[170:173], v[146:149]
	v_mfma_f32_16x16x32_bf16 v[142:145], v[98:101], v[170:173], v[142:145]
	v_mfma_f32_16x16x32_bf16 v[130:133], v[90:93], v[178:181], v[130:133]
	v_mfma_f32_16x16x32_bf16 v[126:129], v[98:101], v[178:181], v[126:129]
	v_mfma_f32_16x16x32_bf16 v[114:117], v[90:93], v[186:189], v[114:117]
	v_mfma_f32_16x16x32_bf16 v[110:113], v[98:101], v[186:189], v[110:113]
	v_mfma_f32_16x16x32_bf16 v[82:85], v[90:93], v[194:197], v[82:85]
	v_mfma_f32_16x16x32_bf16 v[78:81], v[98:101], v[194:197], v[78:81]
	v_mfma_f32_16x16x32_bf16 v[138:141], v[150:153], v[166:169], v[138:141]
	v_mfma_f32_16x16x32_bf16 v[134:137], v[158:161], v[166:169], v[134:137]
	v_mfma_f32_16x16x32_bf16 v[122:125], v[150:153], v[174:177], v[122:125]
	v_mfma_f32_16x16x32_bf16 v[118:121], v[158:161], v[174:177], v[118:121]
	v_mfma_f32_16x16x32_bf16 v[106:109], v[150:153], v[182:185], v[106:109]
	v_mfma_f32_16x16x32_bf16 v[102:105], v[158:161], v[182:185], v[102:105]
	v_mfma_f32_16x16x32_bf16 v[74:77], v[150:153], v[190:193], v[74:77]
	v_mfma_f32_16x16x32_bf16 v[70:73], v[158:161], v[190:193], v[70:73]
	v_mfma_f32_16x16x32_bf16 v[138:141], v[154:157], v[170:173], v[138:141]
	v_mfma_f32_16x16x32_bf16 v[134:137], v[162:165], v[170:173], v[134:137]
	v_mfma_f32_16x16x32_bf16 v[122:125], v[154:157], v[178:181], v[122:125]
	v_mfma_f32_16x16x32_bf16 v[118:121], v[162:165], v[178:181], v[118:121]
	v_mfma_f32_16x16x32_bf16 v[106:109], v[154:157], v[186:189], v[106:109]
	v_mfma_f32_16x16x32_bf16 v[102:105], v[162:165], v[186:189], v[102:105]
	v_mfma_f32_16x16x32_bf16 v[74:77], v[154:157], v[194:197], v[74:77]
	v_mfma_f32_16x16x32_bf16 v[70:73], v[162:165], v[194:197], v[70:73]
	s_barrier
	s_add_i32 s61, s61, s49
	v_lshl_add_u64 v[228:229], s[42:43], 0, v[212:213]
	s_mov_b32 m0, s61
	ds_read_b128 v[166:169], v237 offset:16384
	ds_read_b128 v[170:173], v237 offset:17408
	ds_read_b128 v[174:177], v237 offset:18432
	ds_read_b128 v[178:181], v237 offset:19456
	ds_read_b128 v[182:185], v237 offset:20480
	ds_read_b128 v[186:189], v237 offset:21504
	ds_read_b128 v[190:193], v237 offset:22528
	ds_read_b128 v[194:197], v237 offset:23552
	global_load_lds_dwordx4 v[228:229], off
	s_add_i32 m0, s61, 0x2000
	s_add_u32 s62, s42, 0x80000
	v_lshl_add_u64 v[230:231], s[42:43], 0, v[216:217]
	s_addc_u32 s63, s43, 0
	s_add_i32 s61, s64, s49
	global_load_lds_dwordx4 v[230:231], off
	s_mov_b32 m0, s61
	v_lshl_add_u64 v[240:241], s[44:45], 0, v[214:215]
	global_load_lds_dwordx4 v212, s[62:63]
	s_add_i32 m0, s61, 0x2000
	s_nop 0
	global_load_lds_dwordx4 v216, s[62:63]
	v_lshl_add_u64 v[238:239], s[44:45], 0, v[2:3]
	s_mov_b32 m0, s50
	s_nop 0
	global_load_lds_dwordx4 v[238:239], off
	s_mov_b32 m0, s51
	s_nop 0
	global_load_lds_dwordx4 v[240:241], off
	s_waitcnt vmcnt(8)
	s_waitcnt lgkmcnt(0)
	s_barrier
; #define PG8_STAGE(bufoff, gbase, voff) do { _Pragma("unroll") for (int _i = 0; _i < 2; ++_i) \
;         __builtin_amdgcn_global_load_lds((const unsigned*)((const char*)(gbase) + (voff)[_i]), (LAS unsigned*)(lds + (bufoff) + ldsw + _i * 8192), 16, 0, 0); } while (0)
; #define PG8_LDA(dst, b, h) do { _Pragma("unroll") for (int m = 0; m < 4; ++m) _Pragma("unroll") for (int k = 0; k < 2; ++k) dst[m][k] = *(const LAS bf16x8*)(lds + PG8_SA(b, h) + aoff + m * 2048 + k * 1024); } while (0)
; #define PG8_LDB(dst, b, h) do { _Pragma("unroll") for (int n = 0; n < 2; ++n) _Pragma("unroll") for (int k = 0; k < 2; ++k) dst[n][k] = *(const LAS bf16x8*)(lds + PG8_SB(b, h) + boff + n * 2048 + k * 1024); } while (0)
; #define PG8_MMA(ai, bj, At, Bt) do { __builtin_amdgcn_s_setprio(1); _Pragma("unroll") for (int m = 0; m < 4; ++m) _Pragma("unroll") for (int n = 0; n < 2; ++n) _Pragma("unroll") for (int k = 0; k < 2; ++k) \
;         acc[ai][bj][m][n] = __builtin_amdgcn_mfma_f32_16x16x32_bf16(Bt[n][k], At[m][k], acc[ai][bj][m][n], 0, 0, 0); __builtin_amdgcn_s_setprio(0); } while (0)
; #define PG8_WAIT_V(n) asm volatile("s_waitcnt vmcnt(" #n ")" ::: "memory")
; #define PG8_WAIT_L(n) asm volatile("s_waitcnt lgkmcnt(" #n ")" ::: "memory")
; #define PG8_BAR __builtin_amdgcn_s_barrier()
; #define PG8_SCHED __builtin_amdgcn_sched_barrier(0)
; template <class Epi, class Sched>
; __device__ __forceinline__ void gemm_phase(LAS unsigned char* lds, const Gemm g, const Sched& S, const Epi& E) {
;     ...
;             PG8_WAIT_V(8); PG8_WAIT_L(0); PG8_BAR; PG8_MMA(1, 0, At, B0); PG8_MMA(1, 1, At, B1); PG8_BAR; PG8_SCHED;
;             PG8_LDB(B0, 1, 0); PG8_LDB(B1, 1, 1); PG8_SCHED; PG8_LDA(At, 1, 0); PG8_STAGE(PG8_SA(0, 1), a2 + hstepA, voffA);
;             PG8_WAIT_V(8); PG8_WAIT_L(0); PG8_BAR; PG8_MMA(0, 0, At, B0); PG8_MMA(0, 1, At, B1); PG8_BAR; PG8_SCHED;
	s_waitcnt lgkmcnt(0)
	v_mfma_f32_16x16x32_bf16 v[66:69], v[86:89], v[166:169], v[66:69]
	v_mfma_f32_16x16x32_bf16 v[62:65], v[94:97], v[166:169], v[62:65]
	v_mfma_f32_16x16x32_bf16 v[50:53], v[86:89], v[174:177], v[50:53]
	v_mfma_f32_16x16x32_bf16 v[46:49], v[94:97], v[174:177], v[46:49]
	v_mfma_f32_16x16x32_bf16 v[34:37], v[86:89], v[182:185], v[34:37]
	v_mfma_f32_16x16x32_bf16 v[30:33], v[94:97], v[182:185], v[30:33]
	v_mfma_f32_16x16x32_bf16 v[18:21], v[86:89], v[190:193], v[18:21]
	v_mfma_f32_16x16x32_bf16 v[14:17], v[94:97], v[190:193], v[14:17]
	v_mfma_f32_16x16x32_bf16 v[66:69], v[90:93], v[170:173], v[66:69]
	v_mfma_f32_16x16x32_bf16 v[62:65], v[98:101], v[170:173], v[62:65]
	v_mfma_f32_16x16x32_bf16 v[50:53], v[90:93], v[178:181], v[50:53]
	v_mfma_f32_16x16x32_bf16 v[46:49], v[98:101], v[178:181], v[46:49]
	v_mfma_f32_16x16x32_bf16 v[34:37], v[90:93], v[186:189], v[34:37]
	v_mfma_f32_16x16x32_bf16 v[30:33], v[98:101], v[186:189], v[30:33]
	v_mfma_f32_16x16x32_bf16 v[18:21], v[90:93], v[194:197], v[18:21]
	v_mfma_f32_16x16x32_bf16 v[14:17], v[98:101], v[194:197], v[14:17]
	v_mfma_f32_16x16x32_bf16 v[58:61], v[150:153], v[166:169], v[58:61]
	v_mfma_f32_16x16x32_bf16 v[54:57], v[158:161], v[166:169], v[54:57]
	v_mfma_f32_16x16x32_bf16 v[42:45], v[150:153], v[174:177], v[42:45]
	v_mfma_f32_16x16x32_bf16 v[38:41], v[158:161], v[174:177], v[38:41]
	v_mfma_f32_16x16x32_bf16 v[26:29], v[150:153], v[182:185], v[26:29]
	v_mfma_f32_16x16x32_bf16 v[22:25], v[158:161], v[182:185], v[22:25]
	v_mfma_f32_16x16x32_bf16 v[10:13], v[150:153], v[190:193], v[10:13]
	v_mfma_f32_16x16x32_bf16 v[6:9], v[158:161], v[190:193], v[6:9]
	v_mfma_f32_16x16x32_bf16 v[58:61], v[154:157], v[170:173], v[58:61]
	v_mfma_f32_16x16x32_bf16 v[54:57], v[162:165], v[170:173], v[54:57]
	v_mfma_f32_16x16x32_bf16 v[42:45], v[154:157], v[178:181], v[42:45]
	v_mfma_f32_16x16x32_bf16 v[38:41], v[162:165], v[178:181], v[38:41]
	v_mfma_f32_16x16x32_bf16 v[26:29], v[154:157], v[186:189], v[26:29]
	v_mfma_f32_16x16x32_bf16 v[22:25], v[162:165], v[186:189], v[22:25]
	v_mfma_f32_16x16x32_bf16 v[10:13], v[154:157], v[194:197], v[10:13]
	v_mfma_f32_16x16x32_bf16 v[6:9], v[162:165], v[194:197], v[6:9]
	s_barrier
	s_add_i32 s61, 0, 0x18000
	s_add_i32 s62, 0, 0x1c000
	v_add_u32_e32 v98, s61, v236
	v_add_u32_e32 v162, s62, v236
	ds_read_b128 v[86:89], v98
	ds_read_b128 v[90:93], v98 offset:1024
	ds_read_b128 v[94:97], v98 offset:2048
	ds_read_b128 v[98:101], v98 offset:3072
	ds_read_b128 v[150:153], v162
	ds_read_b128 v[154:157], v162 offset:1024
	ds_read_b128 v[158:161], v162 offset:2048
	ds_read_b128 v[162:165], v162 offset:3072
	s_add_u32 s44, s44, 0x80000
	s_addc_u32 s45, s45, 0
	s_mov_b32 m0, s52
	ds_read_b128 v[166:169], v237 offset:32768
	ds_read_b128 v[170:173], v237 offset:33792
	ds_read_b128 v[174:177], v237 offset:34816
	ds_read_b128 v[178:181], v237 offset:35840
	ds_read_b128 v[182:185], v237 offset:36864
	ds_read_b128 v[186:189], v237 offset:37888
	ds_read_b128 v[190:193], v237 offset:38912
	ds_read_b128 v[194:197], v237 offset:39936
	global_load_lds_dwordx4 v2, s[44:45]
	s_mov_b32 m0, s53
	s_nop 0
	global_load_lds_dwordx4 v214, s[44:45]
	s_waitcnt vmcnt(8)
	s_waitcnt lgkmcnt(0)
	s_barrier
	s_waitcnt lgkmcnt(0)
	v_mfma_f32_16x16x32_bf16 v[146:149], v[86:89], v[166:169], v[146:149]
	v_mfma_f32_16x16x32_bf16 v[142:145], v[94:97], v[166:169], v[142:145]
	v_mfma_f32_16x16x32_bf16 v[130:133], v[86:89], v[174:177], v[130:133]
	v_mfma_f32_16x16x32_bf16 v[126:129], v[94:97], v[174:177], v[126:129]
	v_mfma_f32_16x16x32_bf16 v[114:117], v[86:89], v[182:185], v[114:117]
	v_mfma_f32_16x16x32_bf16 v[110:113], v[94:97], v[182:185], v[110:113]
	v_mfma_f32_16x16x32_bf16 v[82:85], v[86:89], v[190:193], v[82:85]
	v_mfma_f32_16x16x32_bf16 v[78:81], v[94:97], v[190:193], v[78:81]
	v_mfma_f32_16x16x32_bf16 v[146:149], v[90:93], v[170:173], v[146:149]
	v_mfma_f32_16x16x32_bf16 v[142:145], v[98:101], v[170:173], v[142:145]
	v_mfma_f32_16x16x32_bf16 v[130:133], v[90:93], v[178:181], v[130:133]
	v_mfma_f32_16x16x32_bf16 v[126:129], v[98:101], v[178:181], v[126:129]
	v_mfma_f32_16x16x32_bf16 v[114:117], v[90:93], v[186:189], v[114:117]
	v_mfma_f32_16x16x32_bf16 v[110:113], v[98:101], v[186:189], v[110:113]
	v_mfma_f32_16x16x32_bf16 v[82:85], v[90:93], v[194:197], v[82:85]
	v_mfma_f32_16x16x32_bf16 v[78:81], v[98:101], v[194:197], v[78:81]
	v_mfma_f32_16x16x32_bf16 v[138:141], v[150:153], v[166:169], v[138:141]
	v_mfma_f32_16x16x32_bf16 v[134:137], v[158:161], v[166:169], v[134:137]
	v_mfma_f32_16x16x32_bf16 v[122:125], v[150:153], v[174:177], v[122:125]
	v_mfma_f32_16x16x32_bf16 v[118:121], v[158:161], v[174:177], v[118:121]
	v_mfma_f32_16x16x32_bf16 v[106:109], v[150:153], v[182:185], v[106:109]
	v_mfma_f32_16x16x32_bf16 v[102:105], v[158:161], v[182:185], v[102:105]
	v_mfma_f32_16x16x32_bf16 v[74:77], v[150:153], v[190:193], v[74:77]
	v_mfma_f32_16x16x32_bf16 v[70:73], v[158:161], v[190:193], v[70:73]
	v_mfma_f32_16x16x32_bf16 v[138:141], v[154:157], v[170:173], v[138:141]
	v_mfma_f32_16x16x32_bf16 v[134:137], v[162:165], v[170:173], v[134:137]
	v_mfma_f32_16x16x32_bf16 v[122:125], v[154:157], v[178:181], v[122:125]
	v_mfma_f32_16x16x32_bf16 v[118:121], v[162:165], v[178:181], v[118:121]
	v_mfma_f32_16x16x32_bf16 v[106:109], v[154:157], v[186:189], v[106:109]
	v_mfma_f32_16x16x32_bf16 v[102:105], v[162:165], v[186:189], v[102:105]
	v_mfma_f32_16x16x32_bf16 v[74:77], v[154:157], v[194:197], v[74:77]
	v_mfma_f32_16x16x32_bf16 v[70:73], v[162:165], v[194:197], v[70:73]
	s_barrier
; #define PG8_STAGE(bufoff, gbase, voff) do { _Pragma("unroll") for (int _i = 0; _i < 2; ++_i) \
;         __builtin_amdgcn_global_load_lds((const unsigned*)((const char*)(gbase) + (voff)[_i]), (LAS unsigned*)(lds + (bufoff) + ldsw + _i * 8192), 16, 0, 0); } while (0)
; #define PG8_LDA(dst, b, h) do { _Pragma("unroll") for (int m = 0; m < 4; ++m) _Pragma("unroll") for (int k = 0; k < 2; ++k) dst[m][k] = *(const LAS bf16x8*)(lds + PG8_SA(b, h) + aoff + m * 2048 + k * 1024); } while (0)
; #define PG8_MMA(ai, bj, At, Bt) do { __builtin_amdgcn_s_setprio(1); _Pragma("unroll") for (int m = 0; m < 4; ++m) _Pragma("unroll") for (int n = 0; n < 2; ++n) _Pragma("unroll") for (int k = 0; k < 2; ++k) \
;         acc[ai][bj][m][n] = __builtin_amdgcn_mfma_f32_16x16x32_bf16(Bt[n][k], At[m][k], acc[ai][bj][m][n], 0, 0, 0); __builtin_amdgcn_s_setprio(0); } while (0)
; #define PG8_WAIT_V(n) asm volatile("s_waitcnt vmcnt(" #n ")" ::: "memory")
; #define PG8_WAIT_L(n) asm volatile("s_waitcnt lgkmcnt(" #n ")" ::: "memory")
; #define PG8_BAR __builtin_amdgcn_s_barrier()
; #define PG8_SCHED __builtin_amdgcn_sched_barrier(0)
; template <class Epi, class Sched>
; __device__ __forceinline__ void gemm_phase(LAS unsigned char* lds, const Gemm g, const Sched& S, const Epi& E) {
;     ...
;             PG8_LDA(At, 1, 1); PG8_STAGE(PG8_SB(1, 0), b3, voffB); PG8_STAGE(PG8_SB(1, 1), b3 + hstepB, voffB); PG8_STAGE(PG8_SA(1, 0), a3, voffA);
;             PG8_WAIT_V(8); PG8_WAIT_L(0); PG8_BAR; PG8_MMA(1, 0, At, B0); PG8_MMA(1, 1, At, B1); PG8_BAR; PG8_SCHED;
;         }
;         if (wr == 0) PG8_BAR;
	s_add_i32 s44, s61, s49
	v_lshl_add_u64 v[228:229], v[228:229], 0, s[36:37]
	s_mov_b32 m0, s44
	ds_read_b128 v[166:169], v237 offset:49152
	ds_read_b128 v[170:173], v237 offset:50176
	ds_read_b128 v[174:177], v237 offset:51200
	ds_read_b128 v[178:181], v237 offset:52224
	ds_read_b128 v[182:185], v237 offset:53248
	ds_read_b128 v[186:189], v237 offset:54272
	ds_read_b128 v[190:193], v237 offset:55296
	ds_read_b128 v[194:197], v237 offset:56320
	global_load_lds_dwordx4 v[228:229], off
	s_add_i32 m0, s44, 0x2000
	s_add_u32 s42, s42, 0x80080
	v_lshl_add_u64 v[228:229], v[230:231], 0, s[36:37]
	s_addc_u32 s43, s43, 0
	s_add_i32 s44, s62, s49
	global_load_lds_dwordx4 v[228:229], off
	s_mov_b32 m0, s44
	s_nop 0
	global_load_lds_dwordx4 v212, s[42:43]
	s_add_i32 m0, s44, 0x2000
	s_nop 0
	global_load_lds_dwordx4 v216, s[42:43]
	v_lshl_add_u64 v[228:229], v[238:239], 0, s[36:37]
	s_mov_b32 m0, s54
	s_nop 0
	global_load_lds_dwordx4 v[228:229], off
	v_lshl_add_u64 v[228:229], v[240:241], 0, s[36:37]
	s_mov_b32 m0, s55
	s_nop 0
	global_load_lds_dwordx4 v[228:229], off
	s_waitcnt vmcnt(8)
	s_waitcnt lgkmcnt(0)
	s_barrier
	s_waitcnt lgkmcnt(0)
	v_mfma_f32_16x16x32_bf16 v[66:69], v[86:89], v[166:169], v[66:69]
	v_mfma_f32_16x16x32_bf16 v[62:65], v[94:97], v[166:169], v[62:65]
	v_mfma_f32_16x16x32_bf16 v[50:53], v[86:89], v[174:177], v[50:53]
	v_mfma_f32_16x16x32_bf16 v[46:49], v[94:97], v[174:177], v[46:49]
	v_mfma_f32_16x16x32_bf16 v[34:37], v[86:89], v[182:185], v[34:37]
	v_mfma_f32_16x16x32_bf16 v[30:33], v[94:97], v[182:185], v[30:33]
	v_mfma_f32_16x16x32_bf16 v[18:21], v[86:89], v[190:193], v[18:21]
	v_mfma_f32_16x16x32_bf16 v[14:17], v[94:97], v[190:193], v[14:17]
	v_mfma_f32_16x16x32_bf16 v[66:69], v[90:93], v[170:173], v[66:69]
	v_mfma_f32_16x16x32_bf16 v[62:65], v[98:101], v[170:173], v[62:65]
	v_mfma_f32_16x16x32_bf16 v[50:53], v[90:93], v[178:181], v[50:53]
	v_mfma_f32_16x16x32_bf16 v[46:49], v[98:101], v[178:181], v[46:49]
	v_mfma_f32_16x16x32_bf16 v[34:37], v[90:93], v[186:189], v[34:37]
	v_mfma_f32_16x16x32_bf16 v[30:33], v[98:101], v[186:189], v[30:33]
	v_mfma_f32_16x16x32_bf16 v[18:21], v[90:93], v[194:197], v[18:21]
	v_mfma_f32_16x16x32_bf16 v[14:17], v[98:101], v[194:197], v[14:17]
	v_mfma_f32_16x16x32_bf16 v[58:61], v[150:153], v[166:169], v[58:61]
	v_mfma_f32_16x16x32_bf16 v[54:57], v[158:161], v[166:169], v[54:57]
	v_mfma_f32_16x16x32_bf16 v[42:45], v[150:153], v[174:177], v[42:45]
	v_mfma_f32_16x16x32_bf16 v[38:41], v[158:161], v[174:177], v[38:41]
	v_mfma_f32_16x16x32_bf16 v[26:29], v[150:153], v[182:185], v[26:29]
	v_mfma_f32_16x16x32_bf16 v[22:25], v[158:161], v[182:185], v[22:25]
	v_mfma_f32_16x16x32_bf16 v[10:13], v[150:153], v[190:193], v[10:13]
	v_mfma_f32_16x16x32_bf16 v[6:9], v[158:161], v[190:193], v[6:9]
	v_mfma_f32_16x16x32_bf16 v[58:61], v[154:157], v[170:173], v[58:61]
	v_mfma_f32_16x16x32_bf16 v[54:57], v[162:165], v[170:173], v[54:57]
	v_mfma_f32_16x16x32_bf16 v[42:45], v[154:157], v[178:181], v[42:45]
	v_mfma_f32_16x16x32_bf16 v[38:41], v[162:165], v[178:181], v[38:41]
	v_mfma_f32_16x16x32_bf16 v[26:29], v[154:157], v[186:189], v[26:29]
	v_mfma_f32_16x16x32_bf16 v[22:25], v[162:165], v[186:189], v[22:25]
	v_mfma_f32_16x16x32_bf16 v[10:13], v[154:157], v[194:197], v[10:13]
	v_mfma_f32_16x16x32_bf16 v[6:9], v[162:165], v[194:197], v[6:9]
	s_barrier
	s_add_i32 s60, s60, 2
	s_add_u32 s38, s38, 0x100
	s_addc_u32 s39, s39, 0
	s_add_u32 s58, s58, 0x100
	s_addc_u32 s59, s59, 0
	s_cmp_gt_u32 s60, 29
	s_cbranch_scc0 .LBB0_513
	s_and_b64 vcc, exec, s[16:17]
	s_cbranch_vccz .LBB0_516
	s_barrier

; __device__ __forceinline__ float log2_gamma(int hd) { const float e = ldexpf(1.0f, -5 - hd); float p = 1.0f / 7.0f; p = p * e + 1.0f / 6.0f; p = p * e + 0.2f; p = p * e + 0.25f; p = p * e + 1.0f / 3.0f; p = p * e + 0.5f; p = p * e + 1.0f; return -1.44269504089f * e * p; }
; #define PG8_STAGE(bufoff, gbase, voff) do { _Pragma("unroll") for (int _i = 0; _i < 2; ++_i) \
;         __builtin_amdgcn_global_load_lds((const unsigned*)((const char*)(gbase) + (voff)[_i]), (LAS unsigned*)(lds + (bufoff) + ldsw + _i * 8192), 16, 0, 0); } while (0)
; #define PG8_WAIT_V(n) asm volatile("s_waitcnt vmcnt(" #n ")" ::: "memory")
; #define PG8_BAR __builtin_amdgcn_s_barrier()
;     __device__ __forceinline__ void operator()(const f32x4 (&acc)[2][2][4][2], const Unit& u, int wr, int wc, int fr, int fq) const {
;         const int row0 = u.pm * BM + wr * 64 + fr, j0 = wc * 32 + 8 * fq;
;         if (u.pn < 16) {
;             const int hd = u.pn & 7; const bool isq = u.pn < 8;
;             const float l2g = log2_gamma(hd);
;             f32x4 TB[2][6];
; template <class Epi, class Sched>
; __device__ __forceinline__ void gemm_phase(LAS unsigned char* lds, const Gemm g, const Sched& S, const Epi& E) {
;     ...
;     const int aoff = lds_byte(wr * 64 + fr, fq * 8), boff = lds_byte(wc * 32 + fr, fq * 8);
;     ...
;     Unit cur, nxt; int ui = 0;
;     if (!S.next(0, cur)) return;
;     f32x4 acc[2][2][4][2];
; #pragma unroll
;     for (int a = 0; a < 2; ++a)
; #pragma unroll
;         for (int b = 0; b < 2; ++b)
; #pragma unroll
;             for (int m = 0; m < 4; ++m)
; #pragma unroll
;                 for (int n = 0; n < 2; ++n) acc[a][b][m][n] = (f32x4){0.f, 0.f, 0.f, 0.f};
;     bf16x8 At[4][2], B0[2][2], B1[2][2];
;     const char* cA = (const char*)g.A + (size_t)cur.pm * tstepA + (size_t)cur.ka * 2; const char* cB = (const char*)g.Bt + (size_t)cur.pn * tstepB;
;     S.a_ready(cur);
;     PG8_STAGE(PG8_SB(0, 0), cB, voffB); PG8_STAGE(PG8_SB(0, 1), cB + hstepB, voffB); PG8_STAGE(PG8_SA(0, 0), cA, voffA); PG8_STAGE(PG8_SA(0, 1), cA + hstepA, voffA);
;     if (wr == 1) PG8_BAR;
;     PG8_WAIT_V(2); PG8_BAR;
;     PG8_STAGE(PG8_SB(1, 0), cB + kstep, voffB); PG8_STAGE(PG8_SA(1, 0), cA + kstep, voffA); PG8_STAGE(PG8_SB(1, 1), cB + hstepB + kstep, voffB);
;     PG8_WAIT_V(6); PG8_BAR;
.LBB0_649:
	s_add_u32 s8, s14, 0xd000000
	v_lshrrev_b32_e32 v20, 1, v4
	s_addc_u32 s9, s15, 0
	v_and_b32_e32 v189, 15, v4
	v_and_b32_e32 v21, 24, v20
	s_add_u32 s10, s14, 0x100000
	v_lshlrev_b32_e32 v20, 1, v21
	v_lshlrev_b32_e32 v22, 6, v189
	v_lshlrev_b32_e32 v4, 2, v4
	s_addc_u32 s11, s15, 0
	s_and_b32 s18, s13, 3
	v_or_b32_e32 v23, v22, v20
	s_lshl_b32 s13, s16, 13
	v_and_b32_e32 v4, 32, v4
	s_add_i32 m0, s47, 0x18000
	v_lshl_add_u64 v[12:13], v[12:13], 0, s[36:37]
	s_lshl_b32 s51, s16, 6
	v_bitop3_b32 v24, v23, s13, v4 bitop3:0xde
	s_lshl_b32 s13, s18, 12
	s_waitcnt vmcnt(2)
	s_barrier
	global_load_lds_dwordx4 v[12:13], off
	v_lshl_add_u64 v[10:11], v[10:11], 0, s[36:37]
	s_add_i32 m0, s47, 0x1a000
	s_add_i32 s52, s47, 0x8000
	s_add_i32 s53, s47, 0xa000
	global_load_lds_dwordx4 v[10:11], off
	v_lshl_add_u64 v[6:7], v[6:7], 0, s[36:37]
	s_mov_b32 m0, s52
	s_add_u32 s16, s28, 0x80080
	global_load_lds_dwordx4 v[6:7], off
	v_lshl_add_u64 v[6:7], v[8:9], 0, s[36:37]
	s_mov_b32 m0, s53
	s_addc_u32 s17, s29, 0
	global_load_lds_dwordx4 v[6:7], off
	s_add_i32 m0, s47, 0x1c000
	v_lshl_add_u64 v[6:7], s[16:17], 0, v[182:183]
	global_load_lds_dwordx4 v[6:7], off
	v_lshl_add_u64 v[6:7], s[16:17], 0, v[186:187]
	s_add_i32 m0, s47, 0x1e000
	v_lshl_or_b32 v188, s18, 5, v21
	global_load_lds_dwordx4 v[6:7], off
	v_bitop3_b32 v231, v23, s13, v4 bitop3:0xde
	v_lshlrev_b32_e32 v4, 2, v188
	v_lshl_add_u64 v[6:7], s[14:15], 0, v[4:5]
	s_mov_b64 s[16:17], 0x200000
	s_cmpk_lt_u32 s12, 0x100
	v_lshl_add_u64 v[190:191], v[6:7], 0, s[16:17]
	s_mov_b64 s[16:17], 0x600000
	s_cselect_b64 s[12:13], -1, 0
	v_lshl_add_u64 v[192:193], v[6:7], 0, s[16:17]
	s_lshl_b32 s16, s18, 10
	s_add_u32 s14, s14, s16
	s_addc_u32 s15, s15, 0
	v_mov_b32_e32 v23, v5
	v_lshl_add_u64 v[6:7], s[14:15], 0, v[22:23]
	v_mov_b32_e32 v21, v5
	v_lshlrev_b32_e32 v4, 15, v14
	v_lshl_add_u64 v[6:7], v[6:7], 0, v[20:21]
	s_mov_b64 s[14:15], 0x5000000
	v_and_b32_e32 v4, 0xffff0000, v4
	v_lshl_add_u64 v[194:195], v[6:7], 0, s[14:15]
	v_lshl_add_u32 v4, v15, 12, v4
	v_and_b32_e32 v6, 1, v14
	v_lshl_or_b32 v4, v6, 6, v4
	v_lshl_add_u32 v196, v16, 1, v4
	v_lshlrev_b32_e32 v4, 15, v17
	v_and_b32_e32 v4, 0xffff0000, v4
	s_waitcnt vmcnt(6)
	v_lshl_add_u32 v4, v18, 12, v4
	v_and_b32_e32 v6, 1, v17
	v_lshl_or_b32 v4, v6, 6, v4
	v_mov_b32_e32 v197, v5
	v_lshl_add_u32 v212, v19, 1, v4
	v_mov_b32_e32 v213, v5
	s_mov_b32 s54, 0
	v_add_u32_e32 v235, 0, v24
	s_barrier
	s_branch .LBB0_652
	s_nop 0
	s_nop 0
	s_nop 0
	s_nop 0
	s_nop 0
	s_nop 0
	s_nop 0
	s_nop 0
	s_nop 0
	s_nop 0
	s_nop 0
	s_nop 0
	s_nop 0
	s_nop 0
	s_nop 0
	s_nop 0
	s_nop 0
	s_nop 0
	s_nop 0
	s_nop 0
.LBB0_650:
	s_mov_b64 s[22:23], 0

; #define PG8_STAGE(bufoff, gbase, voff) do { _Pragma("unroll") for (int _i = 0; _i < 2; ++_i) \
;         __builtin_amdgcn_global_load_lds((const unsigned*)((const char*)(gbase) + (voff)[_i]), (LAS unsigned*)(lds + (bufoff) + ldsw + _i * 8192), 16, 0, 0); } while (0)
; #define PG8_LDA(dst, b, h) do { _Pragma("unroll") for (int m = 0; m < 4; ++m) _Pragma("unroll") for (int k = 0; k < 2; ++k) dst[m][k] = *(const LAS bf16x8*)(lds + PG8_SA(b, h) + aoff + m * 2048 + k * 1024); } while (0)
; #define PG8_LDB(dst, b, h) do { _Pragma("unroll") for (int n = 0; n < 2; ++n) _Pragma("unroll") for (int k = 0; k < 2; ++k) dst[n][k] = *(const LAS bf16x8*)(lds + PG8_SB(b, h) + boff + n * 2048 + k * 1024); } while (0)
; #define PG8_MMA(ai, bj, At, Bt) do { __builtin_amdgcn_s_setprio(1); _Pragma("unroll") for (int m = 0; m < 4; ++m) _Pragma("unroll") for (int n = 0; n < 2; ++n) _Pragma("unroll") for (int k = 0; k < 2; ++k) \
;         acc[ai][bj][m][n] = __builtin_amdgcn_mfma_f32_16x16x32_bf16(Bt[n][k], At[m][k], acc[ai][bj][m][n], 0, 0, 0); __builtin_amdgcn_s_setprio(0); } while (0)
; #define PG8_WAIT_V(n) asm volatile("s_waitcnt vmcnt(" #n ")" ::: "memory")
; #define PG8_WAIT_L(n) asm volatile("s_waitcnt lgkmcnt(" #n ")" ::: "memory")
; #define PG8_BAR __builtin_amdgcn_s_barrier()
; template <class Epi, class Sched>
; __device__ __forceinline__ void gemm_phase(LAS unsigned char* lds, const Gemm g, const Sched& S, const Epi& E) {
;     ...
;         for (int t = 0; t < nt; t += 2) {
;             const bool last = (t == nt - 2);
;             const char* a1 = cA + (size_t)(t + 1) * kstep;
;             const char* a2 = last ? nA : cA + (size_t)(t + 2) * kstep; const char* b2 = last ? nB : cB + (size_t)(t + 2) * kstep;
;             const char* a3 = a2 + kstep; const char* b3 = b2 + kstep;
;             if (last && has_next) S.a_ready(nxt);
;             PG8_LDB(B0, 0, 0); PG8_LDB(B1, 0, 1); PG8_SCHED; PG8_LDA(At, 0, 0); PG8_STAGE(PG8_SA(1, 1), a1 + hstepA, voffA);
;             PG8_WAIT_V(8); PG8_WAIT_L(0); PG8_BAR; PG8_MMA(0, 0, At, B0); PG8_MMA(0, 1, At, B1); PG8_BAR; PG8_SCHED;
;             PG8_LDA(At, 0, 1); PG8_STAGE(PG8_SB(0, 0), b2, voffB); PG8_STAGE(PG8_SB(0, 1), b2 + hstepB, voffB); PG8_STAGE(PG8_SA(0, 0), a2, voffA);
;             PG8_WAIT_V(8); PG8_WAIT_L(0); PG8_BAR; PG8_MMA(1, 0, At, B0); PG8_MMA(1, 1, At, B1); PG8_BAR; PG8_SCHED;
.LBB0_655:
	s_add_u32 s28, s26, 0xfff80080
	s_addc_u32 s29, s27, -1
	s_add_i32 s57, 0, 0x10000
	s_cmp_eq_u32 s56, 28
	s_cselect_b32 s41, s17, s29
	s_cselect_b32 s40, s23, s28
	v_add_u32_e32 v4, s57, v231
	s_cselect_b32 s29, s15, s55
	s_cselect_b32 s28, s25, s34
	s_add_i32 s60, 0, 0x14000
	ds_read_b128 v[134:137], v4
	ds_read_b128 v[138:141], v4 offset:1024
	ds_read_b128 v[142:145], v4 offset:2048
	ds_read_b128 v[146:149], v4 offset:3072
	v_add_u32_e32 v4, s60, v231
	ds_read_b128 v[150:153], v4
	ds_read_b128 v[154:157], v4 offset:1024
	ds_read_b128 v[158:161], v4 offset:2048
	ds_read_b128 v[162:165], v4 offset:3072
	s_add_i32 m0, s47, 0xc000
	ds_read_b128 v[166:169], v235
	ds_read_b128 v[170:173], v235 offset:1024
	ds_read_b128 v[174:177], v235 offset:2048
	ds_read_b128 v[178:181], v235 offset:3072
	ds_read_b128 v[214:217], v235 offset:4096
	ds_read_b128 v[218:221], v235 offset:5120
	ds_read_b128 v[222:225], v235 offset:6144
	ds_read_b128 v[226:229], v235 offset:7168
	global_load_lds_dwordx4 v196, s[26:27]
	s_add_i32 m0, s47, 0xe000
	s_nop 0
	global_load_lds_dwordx4 v212, s[26:27]
	s_waitcnt vmcnt(8)
	s_waitcnt lgkmcnt(0)
	s_barrier
	s_waitcnt lgkmcnt(0)
	v_mfma_f32_16x16x32_bf16 v[130:133], v[134:137], v[166:169], v[130:133]
	v_mfma_f32_16x16x32_bf16 v[126:129], v[142:145], v[166:169], v[126:129]
	v_mfma_f32_16x16x32_bf16 v[114:117], v[134:137], v[174:177], v[114:117]
	v_mfma_f32_16x16x32_bf16 v[110:113], v[142:145], v[174:177], v[110:113]
	v_mfma_f32_16x16x32_bf16 v[98:101], v[134:137], v[214:217], v[98:101]
	v_mfma_f32_16x16x32_bf16 v[94:97], v[142:145], v[214:217], v[94:97]
	v_mfma_f32_16x16x32_bf16 v[82:85], v[134:137], v[222:225], v[82:85]
	v_mfma_f32_16x16x32_bf16 v[78:81], v[142:145], v[222:225], v[78:81]
	v_mfma_f32_16x16x32_bf16 v[130:133], v[138:141], v[170:173], v[130:133]
	v_mfma_f32_16x16x32_bf16 v[126:129], v[146:149], v[170:173], v[126:129]
	v_mfma_f32_16x16x32_bf16 v[114:117], v[138:141], v[178:181], v[114:117]
	v_mfma_f32_16x16x32_bf16 v[110:113], v[146:149], v[178:181], v[110:113]
	v_mfma_f32_16x16x32_bf16 v[98:101], v[138:141], v[218:221], v[98:101]
	v_mfma_f32_16x16x32_bf16 v[94:97], v[146:149], v[218:221], v[94:97]
	v_mfma_f32_16x16x32_bf16 v[82:85], v[138:141], v[226:229], v[82:85]
	v_mfma_f32_16x16x32_bf16 v[78:81], v[146:149], v[226:229], v[78:81]
	v_mfma_f32_16x16x32_bf16 v[122:125], v[150:153], v[166:169], v[122:125]
	v_mfma_f32_16x16x32_bf16 v[118:121], v[158:161], v[166:169], v[118:121]
	v_mfma_f32_16x16x32_bf16 v[106:109], v[150:153], v[174:177], v[106:109]
	v_mfma_f32_16x16x32_bf16 v[102:105], v[158:161], v[174:177], v[102:105]
	v_mfma_f32_16x16x32_bf16 v[90:93], v[150:153], v[214:217], v[90:93]
	v_mfma_f32_16x16x32_bf16 v[86:89], v[158:161], v[214:217], v[86:89]
	v_mfma_f32_16x16x32_bf16 v[74:77], v[150:153], v[222:225], v[74:77]
	v_mfma_f32_16x16x32_bf16 v[70:73], v[158:161], v[222:225], v[70:73]
	v_mfma_f32_16x16x32_bf16 v[122:125], v[154:157], v[170:173], v[122:125]
	v_mfma_f32_16x16x32_bf16 v[118:121], v[162:165], v[170:173], v[118:121]
	v_mfma_f32_16x16x32_bf16 v[106:109], v[154:157], v[178:181], v[106:109]
	v_mfma_f32_16x16x32_bf16 v[102:105], v[162:165], v[178:181], v[102:105]
	v_mfma_f32_16x16x32_bf16 v[90:93], v[154:157], v[218:221], v[90:93]
	v_mfma_f32_16x16x32_bf16 v[86:89], v[162:165], v[218:221], v[86:89]
	v_mfma_f32_16x16x32_bf16 v[74:77], v[154:157], v[226:229], v[74:77]
	v_mfma_f32_16x16x32_bf16 v[70:73], v[162:165], v[226:229], v[70:73]
	s_barrier
	s_add_i32 s57, s57, s46
	v_lshl_add_u64 v[236:237], s[28:29], 0, v[182:183]
	s_mov_b32 m0, s57
	ds_read_b128 v[166:169], v235 offset:16384
	ds_read_b128 v[170:173], v235 offset:17408
	ds_read_b128 v[174:177], v235 offset:18432
	ds_read_b128 v[178:181], v235 offset:19456
	ds_read_b128 v[214:217], v235 offset:20480
	ds_read_b128 v[218:221], v235 offset:21504
	ds_read_b128 v[222:225], v235 offset:22528
	ds_read_b128 v[226:229], v235 offset:23552
	global_load_lds_dwordx4 v[236:237], off
	s_add_i32 m0, s57, 0x2000
	s_add_u32 s58, s28, 0x80000
	v_lshl_add_u64 v[238:239], s[28:29], 0, v[186:187]
	s_addc_u32 s59, s29, 0
	s_add_i32 s57, s60, s46
	global_load_lds_dwordx4 v[238:239], off
	s_mov_b32 m0, s57
	v_lshl_add_u64 v[242:243], s[40:41], 0, v[184:185]
	global_load_lds_dwordx4 v182, s[58:59]
	s_add_i32 m0, s57, 0x2000
	s_nop 0
	global_load_lds_dwordx4 v186, s[58:59]
	v_lshl_add_u64 v[240:241], s[40:41], 0, v[2:3]
	s_mov_b32 m0, s47
	s_nop 0
	global_load_lds_dwordx4 v[240:241], off
	s_mov_b32 m0, s48
	s_nop 0
	global_load_lds_dwordx4 v[242:243], off
	s_waitcnt vmcnt(8)
	s_waitcnt lgkmcnt(0)
	s_barrier
; #define PG8_STAGE(bufoff, gbase, voff) do { _Pragma("unroll") for (int _i = 0; _i < 2; ++_i) \
;         __builtin_amdgcn_global_load_lds((const unsigned*)((const char*)(gbase) + (voff)[_i]), (LAS unsigned*)(lds + (bufoff) + ldsw + _i * 8192), 16, 0, 0); } while (0)
; #define PG8_LDA(dst, b, h) do { _Pragma("unroll") for (int m = 0; m < 4; ++m) _Pragma("unroll") for (int k = 0; k < 2; ++k) dst[m][k] = *(const LAS bf16x8*)(lds + PG8_SA(b, h) + aoff + m * 2048 + k * 1024); } while (0)
; #define PG8_LDB(dst, b, h) do { _Pragma("unroll") for (int n = 0; n < 2; ++n) _Pragma("unroll") for (int k = 0; k < 2; ++k) dst[n][k] = *(const LAS bf16x8*)(lds + PG8_SB(b, h) + boff + n * 2048 + k * 1024); } while (0)
; #define PG8_MMA(ai, bj, At, Bt) do { __builtin_amdgcn_s_setprio(1); _Pragma("unroll") for (int m = 0; m < 4; ++m) _Pragma("unroll") for (int n = 0; n < 2; ++n) _Pragma("unroll") for (int k = 0; k < 2; ++k) \
;         acc[ai][bj][m][n] = __builtin_amdgcn_mfma_f32_16x16x32_bf16(Bt[n][k], At[m][k], acc[ai][bj][m][n], 0, 0, 0); __builtin_amdgcn_s_setprio(0); } while (0)
; #define PG8_WAIT_V(n) asm volatile("s_waitcnt vmcnt(" #n ")" ::: "memory")
; #define PG8_WAIT_L(n) asm volatile("s_waitcnt lgkmcnt(" #n ")" ::: "memory")
; #define PG8_BAR __builtin_amdgcn_s_barrier()
; #define PG8_SCHED __builtin_amdgcn_sched_barrier(0)
; template <class Epi, class Sched>
; __device__ __forceinline__ void gemm_phase(LAS unsigned char* lds, const Gemm g, const Sched& S, const Epi& E) {
;     ...
;             PG8_WAIT_V(8); PG8_WAIT_L(0); PG8_BAR; PG8_MMA(1, 0, At, B0); PG8_MMA(1, 1, At, B1); PG8_BAR; PG8_SCHED;
;             PG8_LDB(B0, 1, 0); PG8_LDB(B1, 1, 1); PG8_SCHED; PG8_LDA(At, 1, 0); PG8_STAGE(PG8_SA(0, 1), a2 + hstepA, voffA);
;             PG8_WAIT_V(8); PG8_WAIT_L(0); PG8_BAR; PG8_MMA(0, 0, At, B0); PG8_MMA(0, 1, At, B1); PG8_BAR; PG8_SCHED;
	s_waitcnt lgkmcnt(0)
	v_mfma_f32_16x16x32_bf16 v[66:69], v[134:137], v[166:169], v[66:69]
	v_mfma_f32_16x16x32_bf16 v[62:65], v[142:145], v[166:169], v[62:65]
	v_mfma_f32_16x16x32_bf16 v[50:53], v[134:137], v[174:177], v[50:53]
	v_mfma_f32_16x16x32_bf16 v[46:49], v[142:145], v[174:177], v[46:49]
	v_mfma_f32_16x16x32_bf16 v[34:37], v[134:137], v[214:217], v[34:37]
	v_mfma_f32_16x16x32_bf16 v[30:33], v[142:145], v[214:217], v[30:33]
	v_mfma_f32_16x16x32_bf16 v[18:21], v[134:137], v[222:225], v[18:21]
	v_mfma_f32_16x16x32_bf16 v[14:17], v[142:145], v[222:225], v[14:17]
	v_mfma_f32_16x16x32_bf16 v[66:69], v[138:141], v[170:173], v[66:69]
	v_mfma_f32_16x16x32_bf16 v[62:65], v[146:149], v[170:173], v[62:65]
	v_mfma_f32_16x16x32_bf16 v[50:53], v[138:141], v[178:181], v[50:53]
	v_mfma_f32_16x16x32_bf16 v[46:49], v[146:149], v[178:181], v[46:49]
	v_mfma_f32_16x16x32_bf16 v[34:37], v[138:141], v[218:221], v[34:37]
	v_mfma_f32_16x16x32_bf16 v[30:33], v[146:149], v[218:221], v[30:33]
	v_mfma_f32_16x16x32_bf16 v[18:21], v[138:141], v[226:229], v[18:21]
	v_mfma_f32_16x16x32_bf16 v[14:17], v[146:149], v[226:229], v[14:17]
	v_mfma_f32_16x16x32_bf16 v[58:61], v[150:153], v[166:169], v[58:61]
	v_mfma_f32_16x16x32_bf16 v[54:57], v[158:161], v[166:169], v[54:57]
	v_mfma_f32_16x16x32_bf16 v[42:45], v[150:153], v[174:177], v[42:45]
	v_mfma_f32_16x16x32_bf16 v[38:41], v[158:161], v[174:177], v[38:41]
	v_mfma_f32_16x16x32_bf16 v[26:29], v[150:153], v[214:217], v[26:29]
	v_mfma_f32_16x16x32_bf16 v[22:25], v[158:161], v[214:217], v[22:25]
	v_mfma_f32_16x16x32_bf16 v[10:13], v[150:153], v[222:225], v[10:13]
	v_mfma_f32_16x16x32_bf16 v[6:9], v[158:161], v[222:225], v[6:9]
	v_mfma_f32_16x16x32_bf16 v[58:61], v[154:157], v[170:173], v[58:61]
	v_mfma_f32_16x16x32_bf16 v[54:57], v[162:165], v[170:173], v[54:57]
	v_mfma_f32_16x16x32_bf16 v[42:45], v[154:157], v[178:181], v[42:45]
	v_mfma_f32_16x16x32_bf16 v[38:41], v[162:165], v[178:181], v[38:41]
	v_mfma_f32_16x16x32_bf16 v[26:29], v[154:157], v[218:221], v[26:29]
	v_mfma_f32_16x16x32_bf16 v[22:25], v[162:165], v[218:221], v[22:25]
	v_mfma_f32_16x16x32_bf16 v[10:13], v[154:157], v[226:229], v[10:13]
	v_mfma_f32_16x16x32_bf16 v[6:9], v[162:165], v[226:229], v[6:9]
	s_barrier
	s_add_i32 s57, 0, 0x18000
	v_add_u32_e32 v4, s57, v231
	s_add_i32 s58, 0, 0x1c000
	ds_read_b128 v[134:137], v4
	ds_read_b128 v[138:141], v4 offset:1024
	ds_read_b128 v[142:145], v4 offset:2048
	ds_read_b128 v[146:149], v4 offset:3072
	v_add_u32_e32 v4, s58, v231
	ds_read_b128 v[150:153], v4
	ds_read_b128 v[154:157], v4 offset:1024
	ds_read_b128 v[158:161], v4 offset:2048
	ds_read_b128 v[162:165], v4 offset:3072
	s_add_u32 s40, s40, 0x80000
	s_addc_u32 s41, s41, 0
	s_mov_b32 m0, s49
	ds_read_b128 v[166:169], v235 offset:32768
	ds_read_b128 v[170:173], v235 offset:33792
	ds_read_b128 v[174:177], v235 offset:34816
	ds_read_b128 v[178:181], v235 offset:35840
	ds_read_b128 v[214:217], v235 offset:36864
	ds_read_b128 v[218:221], v235 offset:37888
	ds_read_b128 v[222:225], v235 offset:38912
	ds_read_b128 v[226:229], v235 offset:39936
	global_load_lds_dwordx4 v2, s[40:41]
	s_mov_b32 m0, s50
	s_nop 0
	global_load_lds_dwordx4 v184, s[40:41]
	s_waitcnt vmcnt(8)
	s_waitcnt lgkmcnt(0)
	s_barrier
	s_waitcnt lgkmcnt(0)
	v_mfma_f32_16x16x32_bf16 v[130:133], v[134:137], v[166:169], v[130:133]
	v_mfma_f32_16x16x32_bf16 v[126:129], v[142:145], v[166:169], v[126:129]
	v_mfma_f32_16x16x32_bf16 v[114:117], v[134:137], v[174:177], v[114:117]
	v_mfma_f32_16x16x32_bf16 v[110:113], v[142:145], v[174:177], v[110:113]
	v_mfma_f32_16x16x32_bf16 v[98:101], v[134:137], v[214:217], v[98:101]
	v_mfma_f32_16x16x32_bf16 v[94:97], v[142:145], v[214:217], v[94:97]
	v_mfma_f32_16x16x32_bf16 v[82:85], v[134:137], v[222:225], v[82:85]
	v_mfma_f32_16x16x32_bf16 v[78:81], v[142:145], v[222:225], v[78:81]
	v_mfma_f32_16x16x32_bf16 v[130:133], v[138:141], v[170:173], v[130:133]
	v_mfma_f32_16x16x32_bf16 v[126:129], v[146:149], v[170:173], v[126:129]
	v_mfma_f32_16x16x32_bf16 v[114:117], v[138:141], v[178:181], v[114:117]
	v_mfma_f32_16x16x32_bf16 v[110:113], v[146:149], v[178:181], v[110:113]
	v_mfma_f32_16x16x32_bf16 v[98:101], v[138:141], v[218:221], v[98:101]
	v_mfma_f32_16x16x32_bf16 v[94:97], v[146:149], v[218:221], v[94:97]
	v_mfma_f32_16x16x32_bf16 v[82:85], v[138:141], v[226:229], v[82:85]
	v_mfma_f32_16x16x32_bf16 v[78:81], v[146:149], v[226:229], v[78:81]
	v_mfma_f32_16x16x32_bf16 v[122:125], v[150:153], v[166:169], v[122:125]
	v_mfma_f32_16x16x32_bf16 v[118:121], v[158:161], v[166:169], v[118:121]
	v_mfma_f32_16x16x32_bf16 v[106:109], v[150:153], v[174:177], v[106:109]
	v_mfma_f32_16x16x32_bf16 v[102:105], v[158:161], v[174:177], v[102:105]
	v_mfma_f32_16x16x32_bf16 v[90:93], v[150:153], v[214:217], v[90:93]
	v_mfma_f32_16x16x32_bf16 v[86:89], v[158:161], v[214:217], v[86:89]
	v_mfma_f32_16x16x32_bf16 v[74:77], v[150:153], v[222:225], v[74:77]
	v_mfma_f32_16x16x32_bf16 v[70:73], v[158:161], v[222:225], v[70:73]
	v_mfma_f32_16x16x32_bf16 v[122:125], v[154:157], v[170:173], v[122:125]
	v_mfma_f32_16x16x32_bf16 v[118:121], v[162:165], v[170:173], v[118:121]
	v_mfma_f32_16x16x32_bf16 v[106:109], v[154:157], v[178:181], v[106:109]
	v_mfma_f32_16x16x32_bf16 v[102:105], v[162:165], v[178:181], v[102:105]
	v_mfma_f32_16x16x32_bf16 v[90:93], v[154:157], v[218:221], v[90:93]
	v_mfma_f32_16x16x32_bf16 v[86:89], v[162:165], v[218:221], v[86:89]
	v_mfma_f32_16x16x32_bf16 v[74:77], v[154:157], v[226:229], v[74:77]
	v_mfma_f32_16x16x32_bf16 v[70:73], v[162:165], v[226:229], v[70:73]
	s_barrier
; #define PG8_STAGE(bufoff, gbase, voff) do { _Pragma("unroll") for (int _i = 0; _i < 2; ++_i) \
;         __builtin_amdgcn_global_load_lds((const unsigned*)((const char*)(gbase) + (voff)[_i]), (LAS unsigned*)(lds + (bufoff) + ldsw + _i * 8192), 16, 0, 0); } while (0)
; #define PG8_LDA(dst, b, h) do { _Pragma("unroll") for (int m = 0; m < 4; ++m) _Pragma("unroll") for (int k = 0; k < 2; ++k) dst[m][k] = *(const LAS bf16x8*)(lds + PG8_SA(b, h) + aoff + m * 2048 + k * 1024); } while (0)
; #define PG8_MMA(ai, bj, At, Bt) do { __builtin_amdgcn_s_setprio(1); _Pragma("unroll") for (int m = 0; m < 4; ++m) _Pragma("unroll") for (int n = 0; n < 2; ++n) _Pragma("unroll") for (int k = 0; k < 2; ++k) \
;         acc[ai][bj][m][n] = __builtin_amdgcn_mfma_f32_16x16x32_bf16(Bt[n][k], At[m][k], acc[ai][bj][m][n], 0, 0, 0); __builtin_amdgcn_s_setprio(0); } while (0)
; #define PG8_WAIT_V(n) asm volatile("s_waitcnt vmcnt(" #n ")" ::: "memory")
; #define PG8_WAIT_L(n) asm volatile("s_waitcnt lgkmcnt(" #n ")" ::: "memory")
; #define PG8_BAR __builtin_amdgcn_s_barrier()
; #define PG8_SCHED __builtin_amdgcn_sched_barrier(0)
; template <class Epi, class Sched>
; __device__ __forceinline__ void gemm_phase(LAS unsigned char* lds, const Gemm g, const Sched& S, const Epi& E) {
;     ...
;             PG8_LDA(At, 1, 1); PG8_STAGE(PG8_SB(1, 0), b3, voffB); PG8_STAGE(PG8_SB(1, 1), b3 + hstepB, voffB); PG8_STAGE(PG8_SA(1, 0), a3, voffA);
;             PG8_WAIT_V(8); PG8_WAIT_L(0); PG8_BAR; PG8_MMA(1, 0, At, B0); PG8_MMA(1, 1, At, B1); PG8_BAR; PG8_SCHED;
;         }
;         if (wr == 0) PG8_BAR;
	s_add_i32 s40, s57, s46
	v_lshl_add_u64 v[236:237], v[236:237], 0, s[36:37]
	s_mov_b32 m0, s40
	ds_read_b128 v[166:169], v235 offset:49152
	ds_read_b128 v[170:173], v235 offset:50176
	ds_read_b128 v[174:177], v235 offset:51200
	ds_read_b128 v[178:181], v235 offset:52224
	ds_read_b128 v[214:217], v235 offset:53248
	ds_read_b128 v[218:221], v235 offset:54272
	ds_read_b128 v[222:225], v235 offset:55296
	ds_read_b128 v[226:229], v235 offset:56320
	global_load_lds_dwordx4 v[236:237], off
	s_add_i32 m0, s40, 0x2000
	s_add_u32 s28, s28, 0x80080
	v_lshl_add_u64 v[236:237], v[238:239], 0, s[36:37]
	s_addc_u32 s29, s29, 0
	s_add_i32 s40, s58, s46
	global_load_lds_dwordx4 v[236:237], off
	s_mov_b32 m0, s40
	s_nop 0
	global_load_lds_dwordx4 v182, s[28:29]
	s_add_i32 m0, s40, 0x2000
	s_nop 0
	global_load_lds_dwordx4 v186, s[28:29]
	v_lshl_add_u64 v[236:237], v[240:241], 0, s[36:37]
	s_mov_b32 m0, s52
	s_nop 0
	global_load_lds_dwordx4 v[236:237], off
	v_lshl_add_u64 v[236:237], v[242:243], 0, s[36:37]
	s_mov_b32 m0, s53
	s_nop 0
	global_load_lds_dwordx4 v[236:237], off
	s_waitcnt vmcnt(8)
	s_waitcnt lgkmcnt(0)
	s_barrier
	s_waitcnt lgkmcnt(0)
	v_mfma_f32_16x16x32_bf16 v[66:69], v[134:137], v[166:169], v[66:69]
	v_mfma_f32_16x16x32_bf16 v[62:65], v[142:145], v[166:169], v[62:65]
	v_mfma_f32_16x16x32_bf16 v[50:53], v[134:137], v[174:177], v[50:53]
	v_mfma_f32_16x16x32_bf16 v[46:49], v[142:145], v[174:177], v[46:49]
	v_mfma_f32_16x16x32_bf16 v[34:37], v[134:137], v[214:217], v[34:37]
	v_mfma_f32_16x16x32_bf16 v[30:33], v[142:145], v[214:217], v[30:33]
	v_mfma_f32_16x16x32_bf16 v[18:21], v[134:137], v[222:225], v[18:21]
	v_mfma_f32_16x16x32_bf16 v[14:17], v[142:145], v[222:225], v[14:17]
	v_mfma_f32_16x16x32_bf16 v[66:69], v[138:141], v[170:173], v[66:69]
	v_mfma_f32_16x16x32_bf16 v[62:65], v[146:149], v[170:173], v[62:65]
	v_mfma_f32_16x16x32_bf16 v[50:53], v[138:141], v[178:181], v[50:53]
	v_mfma_f32_16x16x32_bf16 v[46:49], v[146:149], v[178:181], v[46:49]
	v_mfma_f32_16x16x32_bf16 v[34:37], v[138:141], v[218:221], v[34:37]
	v_mfma_f32_16x16x32_bf16 v[30:33], v[146:149], v[218:221], v[30:33]
	v_mfma_f32_16x16x32_bf16 v[18:21], v[138:141], v[226:229], v[18:21]
	v_mfma_f32_16x16x32_bf16 v[14:17], v[146:149], v[226:229], v[14:17]
	v_mfma_f32_16x16x32_bf16 v[58:61], v[150:153], v[166:169], v[58:61]
	v_mfma_f32_16x16x32_bf16 v[54:57], v[158:161], v[166:169], v[54:57]
	v_mfma_f32_16x16x32_bf16 v[42:45], v[150:153], v[174:177], v[42:45]
	v_mfma_f32_16x16x32_bf16 v[38:41], v[158:161], v[174:177], v[38:41]
	v_mfma_f32_16x16x32_bf16 v[26:29], v[150:153], v[214:217], v[26:29]
	v_mfma_f32_16x16x32_bf16 v[22:25], v[158:161], v[214:217], v[22:25]
	v_mfma_f32_16x16x32_bf16 v[10:13], v[150:153], v[222:225], v[10:13]
	v_mfma_f32_16x16x32_bf16 v[6:9], v[158:161], v[222:225], v[6:9]
	v_mfma_f32_16x16x32_bf16 v[58:61], v[154:157], v[170:173], v[58:61]
	v_mfma_f32_16x16x32_bf16 v[54:57], v[162:165], v[170:173], v[54:57]
	v_mfma_f32_16x16x32_bf16 v[42:45], v[154:157], v[178:181], v[42:45]
	v_mfma_f32_16x16x32_bf16 v[38:41], v[162:165], v[178:181], v[38:41]
	v_mfma_f32_16x16x32_bf16 v[26:29], v[154:157], v[218:221], v[26:29]
	v_mfma_f32_16x16x32_bf16 v[22:25], v[162:165], v[218:221], v[22:25]
	v_mfma_f32_16x16x32_bf16 v[10:13], v[154:157], v[226:229], v[10:13]
	v_mfma_f32_16x16x32_bf16 v[6:9], v[162:165], v[226:229], v[6:9]
	s_barrier
	s_add_i32 s56, s56, 2
	s_add_u32 s26, s26, 0x100
	s_addc_u32 s27, s27, 0
	s_add_u32 s34, s34, 0x100
	s_addc_u32 s55, s55, 0
	s_cmp_gt_u32 s56, 29
	s_cbranch_scc0 .LBB0_655
	s_and_b64 vcc, exec, s[12:13]
	s_cbranch_vccz .LBB0_658
	s_barrier

; #define PG8_STAGE(bufoff, gbase, voff) do { _Pragma("unroll") for (int _i = 0; _i < 2; ++_i) \
;         __builtin_amdgcn_global_load_lds((const unsigned*)((const char*)(gbase) + (voff)[_i]), (LAS unsigned*)(lds + (bufoff) + ldsw + _i * 8192), 16, 0, 0); } while (0)
; #define PG8_LDA(dst, b, h) do { _Pragma("unroll") for (int m = 0; m < 4; ++m) _Pragma("unroll") for (int k = 0; k < 2; ++k) dst[m][k] = *(const LAS bf16x8*)(lds + PG8_SA(b, h) + aoff + m * 2048 + k * 1024); } while (0)
; #define PG8_LDB(dst, b, h) do { _Pragma("unroll") for (int n = 0; n < 2; ++n) _Pragma("unroll") for (int k = 0; k < 2; ++k) dst[n][k] = *(const LAS bf16x8*)(lds + PG8_SB(b, h) + boff + n * 2048 + k * 1024); } while (0)
; #define PG8_MMA(ai, bj, At, Bt) do { __builtin_amdgcn_s_setprio(1); _Pragma("unroll") for (int m = 0; m < 4; ++m) _Pragma("unroll") for (int n = 0; n < 2; ++n) _Pragma("unroll") for (int k = 0; k < 2; ++k) \
;         acc[ai][bj][m][n] = __builtin_amdgcn_mfma_f32_16x16x32_bf16(Bt[n][k], At[m][k], acc[ai][bj][m][n], 0, 0, 0); __builtin_amdgcn_s_setprio(0); } while (0)
; #define PG8_WAIT_V(n) asm volatile("s_waitcnt vmcnt(" #n ")" ::: "memory")
; #define PG8_WAIT_L(n) asm volatile("s_waitcnt lgkmcnt(" #n ")" ::: "memory")
; #define PG8_BAR __builtin_amdgcn_s_barrier()
; template <class Epi, class Sched>
; __device__ __forceinline__ void gemm_phase(LAS unsigned char* lds, const Gemm g, const Sched& S, const Epi& E) {
;     ...
;         for (int t = 0; t < nt; t += 2) {
;             const bool last = (t == nt - 2);
;             const char* a1 = cA + (size_t)(t + 1) * kstep;
;             const char* a2 = last ? nA : cA + (size_t)(t + 2) * kstep; const char* b2 = last ? nB : cB + (size_t)(t + 2) * kstep;
;             const char* a3 = a2 + kstep; const char* b3 = b2 + kstep;
;             if (last && has_next) S.a_ready(nxt);
;             PG8_LDB(B0, 0, 0); PG8_LDB(B1, 0, 1); PG8_SCHED; PG8_LDA(At, 0, 0); PG8_STAGE(PG8_SA(1, 1), a1 + hstepA, voffA);
;             PG8_WAIT_V(8); PG8_WAIT_L(0); PG8_BAR; PG8_MMA(0, 0, At, B0); PG8_MMA(0, 1, At, B1); PG8_BAR; PG8_SCHED;
;             PG8_LDA(At, 0, 1); PG8_STAGE(PG8_SB(0, 0), b2, voffB); PG8_STAGE(PG8_SB(0, 1), b2 + hstepB, voffB); PG8_STAGE(PG8_SA(0, 0), a2, voffA);
;             PG8_WAIT_V(8); PG8_WAIT_L(0); PG8_BAR; PG8_MMA(1, 0, At, B0); PG8_MMA(1, 1, At, B1); PG8_BAR; PG8_SCHED;
.LBB0_1009:
	s_add_i32 s43, s48, 2
	s_add_u32 s70, s26, s46
	s_addc_u32 s49, s27, s47
	s_add_u32 s72, s24, s46
	s_addc_u32 s71, s25, s47
	s_add_i32 s73, 0, 0x10000
	s_cmp_eq_u32 s65, s48
	s_cselect_b32 s49, s5, s49
	s_cselect_b32 s48, s4, s70
	v_add_u32_e32 v4, s73, v148
	s_cselect_b32 s71, s45, s71
	s_cselect_b32 s70, s44, s72
	s_add_i32 s72, 0, 0x14000
	ds_read_b128 v[150:153], v4
	ds_read_b128 v[154:157], v4 offset:1024
	ds_read_b128 v[158:161], v4 offset:2048
	ds_read_b128 v[162:165], v4 offset:3072
	v_add_u32_e32 v4, s72, v148
	ds_read_b128 v[170:173], v4
	ds_read_b128 v[174:177], v4 offset:1024
	ds_read_b128 v[178:181], v4 offset:2048
	ds_read_b128 v[182:185], v4 offset:3072
	v_lshl_add_u64 v[166:167], s[26:27], 0, v[146:147]
	s_add_i32 m0, s58, 0xc000
	ds_read_b128 v[186:189], v149
	ds_read_b128 v[190:193], v149 offset:1024
	ds_read_b128 v[194:197], v149 offset:2048
	ds_read_b128 v[212:215], v149 offset:3072
	ds_read_b128 v[216:219], v149 offset:4096
	ds_read_b128 v[220:223], v149 offset:5120
	ds_read_b128 v[224:227], v149 offset:6144
	ds_read_b128 v[228:231], v149 offset:7168
	global_load_lds_dwordx4 v[166:167], off
	v_lshl_add_u64 v[166:167], s[26:27], 0, v[2:3]
	s_add_i32 m0, s58, 0xe000
	s_nop 0
	global_load_lds_dwordx4 v[166:167], off
	s_waitcnt vmcnt(8)
	s_waitcnt lgkmcnt(0)
	s_barrier
	s_waitcnt lgkmcnt(0)
	v_mfma_f32_16x16x32_bf16 v[130:133], v[150:153], v[186:189], v[130:133]
	v_mfma_f32_16x16x32_bf16 v[126:129], v[158:161], v[186:189], v[126:129]
	v_mfma_f32_16x16x32_bf16 v[122:125], v[150:153], v[194:197], v[122:125]
	v_mfma_f32_16x16x32_bf16 v[118:121], v[158:161], v[194:197], v[118:121]
	v_mfma_f32_16x16x32_bf16 v[110:113], v[150:153], v[216:219], v[110:113]
	v_mfma_f32_16x16x32_bf16 v[106:109], v[158:161], v[216:219], v[106:109]
	v_mfma_f32_16x16x32_bf16 v[98:101], v[150:153], v[224:227], v[98:101]
	v_mfma_f32_16x16x32_bf16 v[90:93], v[158:161], v[224:227], v[90:93]
	v_mfma_f32_16x16x32_bf16 v[130:133], v[154:157], v[190:193], v[130:133]
	v_mfma_f32_16x16x32_bf16 v[126:129], v[162:165], v[190:193], v[126:129]
	v_mfma_f32_16x16x32_bf16 v[122:125], v[154:157], v[212:215], v[122:125]
	v_mfma_f32_16x16x32_bf16 v[118:121], v[162:165], v[212:215], v[118:121]
	v_mfma_f32_16x16x32_bf16 v[110:113], v[154:157], v[220:223], v[110:113]
	v_mfma_f32_16x16x32_bf16 v[106:109], v[162:165], v[220:223], v[106:109]
	v_mfma_f32_16x16x32_bf16 v[98:101], v[154:157], v[228:231], v[98:101]
	v_mfma_f32_16x16x32_bf16 v[90:93], v[162:165], v[228:231], v[90:93]
	v_mfma_f32_16x16x32_bf16 v[114:117], v[170:173], v[186:189], v[114:117]
	v_mfma_f32_16x16x32_bf16 v[102:105], v[178:181], v[186:189], v[102:105]
	v_mfma_f32_16x16x32_bf16 v[94:97], v[170:173], v[194:197], v[94:97]
	v_mfma_f32_16x16x32_bf16 v[86:89], v[178:181], v[194:197], v[86:89]
	v_mfma_f32_16x16x32_bf16 v[82:85], v[170:173], v[216:219], v[82:85]
	v_mfma_f32_16x16x32_bf16 v[78:81], v[178:181], v[216:219], v[78:81]
	v_mfma_f32_16x16x32_bf16 v[74:77], v[170:173], v[224:227], v[74:77]
	v_mfma_f32_16x16x32_bf16 v[70:73], v[178:181], v[224:227], v[70:73]
	v_mfma_f32_16x16x32_bf16 v[114:117], v[174:177], v[190:193], v[114:117]
	v_mfma_f32_16x16x32_bf16 v[102:105], v[182:185], v[190:193], v[102:105]
	v_mfma_f32_16x16x32_bf16 v[94:97], v[174:177], v[212:215], v[94:97]
	v_mfma_f32_16x16x32_bf16 v[86:89], v[182:185], v[212:215], v[86:89]
	v_mfma_f32_16x16x32_bf16 v[82:85], v[174:177], v[220:223], v[82:85]
	v_mfma_f32_16x16x32_bf16 v[78:81], v[182:185], v[220:223], v[78:81]
	v_mfma_f32_16x16x32_bf16 v[74:77], v[174:177], v[228:231], v[74:77]
	v_mfma_f32_16x16x32_bf16 v[70:73], v[182:185], v[228:231], v[70:73]
	s_barrier
	s_add_i32 s73, s73, s57
	v_lshl_add_u64 v[166:167], s[70:71], 0, v[138:139]
	s_mov_b32 m0, s73
	ds_read_b128 v[186:189], v149 offset:16384
	ds_read_b128 v[190:193], v149 offset:17408
	ds_read_b128 v[194:197], v149 offset:18432
	ds_read_b128 v[212:215], v149 offset:19456
	ds_read_b128 v[216:219], v149 offset:20480
	ds_read_b128 v[220:223], v149 offset:21504
	ds_read_b128 v[224:227], v149 offset:22528
	ds_read_b128 v[228:231], v149 offset:23552
	global_load_lds_dwordx4 v[166:167], off
	s_add_i32 m0, s73, 0x2000
	v_lshl_add_u64 v[236:237], s[70:71], 0, v[134:135]
	s_add_u32 s70, s70, s55
	s_addc_u32 s71, s71, 0
	s_add_i32 s72, s72, s57
	global_load_lds_dwordx4 v[236:237], off
	v_lshl_add_u64 v[238:239], s[70:71], 0, v[138:139]
	s_mov_b32 m0, s72
	v_lshl_add_u64 v[240:241], s[70:71], 0, v[134:135]
	global_load_lds_dwordx4 v[238:239], off
	s_add_i32 m0, s72, 0x2000
	v_lshl_add_u64 v[242:243], s[48:49], 0, v[140:141]
	global_load_lds_dwordx4 v[240:241], off
	s_mov_b32 m0, s58
	v_lshl_add_u64 v[244:245], s[48:49], 0, v[136:137]
	global_load_lds_dwordx4 v[242:243], off
	s_mov_b32 m0, s59
	s_nop 0
	global_load_lds_dwordx4 v[244:245], off
	s_waitcnt vmcnt(8)
	s_waitcnt lgkmcnt(0)
	s_barrier
; #define PG8_STAGE(bufoff, gbase, voff) do { _Pragma("unroll") for (int _i = 0; _i < 2; ++_i) \
;         __builtin_amdgcn_global_load_lds((const unsigned*)((const char*)(gbase) + (voff)[_i]), (LAS unsigned*)(lds + (bufoff) + ldsw + _i * 8192), 16, 0, 0); } while (0)
; #define PG8_LDA(dst, b, h) do { _Pragma("unroll") for (int m = 0; m < 4; ++m) _Pragma("unroll") for (int k = 0; k < 2; ++k) dst[m][k] = *(const LAS bf16x8*)(lds + PG8_SA(b, h) + aoff + m * 2048 + k * 1024); } while (0)
; #define PG8_LDB(dst, b, h) do { _Pragma("unroll") for (int n = 0; n < 2; ++n) _Pragma("unroll") for (int k = 0; k < 2; ++k) dst[n][k] = *(const LAS bf16x8*)(lds + PG8_SB(b, h) + boff + n * 2048 + k * 1024); } while (0)
; #define PG8_MMA(ai, bj, At, Bt) do { __builtin_amdgcn_s_setprio(1); _Pragma("unroll") for (int m = 0; m < 4; ++m) _Pragma("unroll") for (int n = 0; n < 2; ++n) _Pragma("unroll") for (int k = 0; k < 2; ++k) \
;         acc[ai][bj][m][n] = __builtin_amdgcn_mfma_f32_16x16x32_bf16(Bt[n][k], At[m][k], acc[ai][bj][m][n], 0, 0, 0); __builtin_amdgcn_s_setprio(0); } while (0)
; #define PG8_WAIT_V(n) asm volatile("s_waitcnt vmcnt(" #n ")" ::: "memory")
; #define PG8_WAIT_L(n) asm volatile("s_waitcnt lgkmcnt(" #n ")" ::: "memory")
; #define PG8_BAR __builtin_amdgcn_s_barrier()
; #define PG8_SCHED __builtin_amdgcn_sched_barrier(0)
; template <class Epi, class Sched>
; __device__ __forceinline__ void gemm_phase(LAS unsigned char* lds, const Gemm g, const Sched& S, const Epi& E) {
;     ...
;             PG8_WAIT_V(8); PG8_WAIT_L(0); PG8_BAR; PG8_MMA(1, 0, At, B0); PG8_MMA(1, 1, At, B1); PG8_BAR; PG8_SCHED;
;             PG8_LDB(B0, 1, 0); PG8_LDB(B1, 1, 1); PG8_SCHED; PG8_LDA(At, 1, 0); PG8_STAGE(PG8_SA(0, 1), a2 + hstepA, voffA);
;             PG8_WAIT_V(8); PG8_WAIT_L(0); PG8_BAR; PG8_MMA(0, 0, At, B0); PG8_MMA(0, 1, At, B1); PG8_BAR; PG8_SCHED;
	s_waitcnt lgkmcnt(0)
	v_mfma_f32_16x16x32_bf16 v[66:69], v[150:153], v[186:189], v[66:69]
	v_mfma_f32_16x16x32_bf16 v[62:65], v[158:161], v[186:189], v[62:65]
	v_mfma_f32_16x16x32_bf16 v[58:61], v[150:153], v[194:197], v[58:61]
	v_mfma_f32_16x16x32_bf16 v[54:57], v[158:161], v[194:197], v[54:57]
	v_mfma_f32_16x16x32_bf16 v[50:53], v[150:153], v[216:219], v[50:53]
	v_mfma_f32_16x16x32_bf16 v[42:45], v[158:161], v[216:219], v[42:45]
	v_mfma_f32_16x16x32_bf16 v[34:37], v[150:153], v[224:227], v[34:37]
	v_mfma_f32_16x16x32_bf16 v[26:29], v[158:161], v[224:227], v[26:29]
	v_mfma_f32_16x16x32_bf16 v[66:69], v[154:157], v[190:193], v[66:69]
	v_mfma_f32_16x16x32_bf16 v[62:65], v[162:165], v[190:193], v[62:65]
	v_mfma_f32_16x16x32_bf16 v[58:61], v[154:157], v[212:215], v[58:61]
	v_mfma_f32_16x16x32_bf16 v[54:57], v[162:165], v[212:215], v[54:57]
	v_mfma_f32_16x16x32_bf16 v[50:53], v[154:157], v[220:223], v[50:53]
	v_mfma_f32_16x16x32_bf16 v[42:45], v[162:165], v[220:223], v[42:45]
	v_mfma_f32_16x16x32_bf16 v[34:37], v[154:157], v[228:231], v[34:37]
	v_mfma_f32_16x16x32_bf16 v[26:29], v[162:165], v[228:231], v[26:29]
	v_mfma_f32_16x16x32_bf16 v[46:49], v[170:173], v[186:189], v[46:49]
	v_mfma_f32_16x16x32_bf16 v[38:41], v[178:181], v[186:189], v[38:41]
	v_mfma_f32_16x16x32_bf16 v[30:33], v[170:173], v[194:197], v[30:33]
	v_mfma_f32_16x16x32_bf16 v[22:25], v[178:181], v[194:197], v[22:25]
	v_mfma_f32_16x16x32_bf16 v[18:21], v[170:173], v[216:219], v[18:21]
	v_mfma_f32_16x16x32_bf16 v[14:17], v[178:181], v[216:219], v[14:17]
	v_mfma_f32_16x16x32_bf16 v[10:13], v[170:173], v[224:227], v[10:13]
	v_mfma_f32_16x16x32_bf16 v[6:9], v[178:181], v[224:227], v[6:9]
	v_mfma_f32_16x16x32_bf16 v[46:49], v[174:177], v[190:193], v[46:49]
	v_mfma_f32_16x16x32_bf16 v[38:41], v[182:185], v[190:193], v[38:41]
	v_mfma_f32_16x16x32_bf16 v[30:33], v[174:177], v[212:215], v[30:33]
	v_mfma_f32_16x16x32_bf16 v[22:25], v[182:185], v[212:215], v[22:25]
	v_mfma_f32_16x16x32_bf16 v[18:21], v[174:177], v[220:223], v[18:21]
	v_mfma_f32_16x16x32_bf16 v[14:17], v[182:185], v[220:223], v[14:17]
	v_mfma_f32_16x16x32_bf16 v[10:13], v[174:177], v[228:231], v[10:13]
	v_mfma_f32_16x16x32_bf16 v[6:9], v[182:185], v[228:231], v[6:9]
	s_barrier
	s_add_i32 s70, 0, 0x18000
	v_add_u32_e32 v4, s70, v148
	s_add_i32 s71, 0, 0x1c000
	ds_read_b128 v[150:153], v4
	ds_read_b128 v[154:157], v4 offset:1024
	ds_read_b128 v[158:161], v4 offset:2048
	ds_read_b128 v[162:165], v4 offset:3072
	v_add_u32_e32 v4, s71, v148
	ds_read_b128 v[170:173], v4
	ds_read_b128 v[174:177], v4 offset:1024
	ds_read_b128 v[178:181], v4 offset:2048
	ds_read_b128 v[182:185], v4 offset:3072
	s_add_u32 s48, s48, s34
	s_addc_u32 s49, s49, 0
	s_mov_b32 m0, s60
	ds_read_b128 v[186:189], v149 offset:32768
	ds_read_b128 v[190:193], v149 offset:33792
	ds_read_b128 v[194:197], v149 offset:34816
	ds_read_b128 v[212:215], v149 offset:35840
	ds_read_b128 v[216:219], v149 offset:36864
	ds_read_b128 v[220:223], v149 offset:37888
	ds_read_b128 v[224:227], v149 offset:38912
	ds_read_b128 v[228:231], v149 offset:39936
	global_load_lds_dwordx4 v140, s[48:49]
	s_mov_b32 m0, s61
	s_nop 0
	global_load_lds_dwordx4 v136, s[48:49]
	s_waitcnt vmcnt(8)
	s_waitcnt lgkmcnt(0)
	s_barrier
	s_waitcnt lgkmcnt(0)
	v_mfma_f32_16x16x32_bf16 v[130:133], v[150:153], v[186:189], v[130:133]
	v_mfma_f32_16x16x32_bf16 v[126:129], v[158:161], v[186:189], v[126:129]
	v_mfma_f32_16x16x32_bf16 v[122:125], v[150:153], v[194:197], v[122:125]
	v_mfma_f32_16x16x32_bf16 v[118:121], v[158:161], v[194:197], v[118:121]
	v_mfma_f32_16x16x32_bf16 v[110:113], v[150:153], v[216:219], v[110:113]
	v_mfma_f32_16x16x32_bf16 v[106:109], v[158:161], v[216:219], v[106:109]
	v_mfma_f32_16x16x32_bf16 v[98:101], v[150:153], v[224:227], v[98:101]
	v_mfma_f32_16x16x32_bf16 v[90:93], v[158:161], v[224:227], v[90:93]
	v_mfma_f32_16x16x32_bf16 v[130:133], v[154:157], v[190:193], v[130:133]
	v_mfma_f32_16x16x32_bf16 v[126:129], v[162:165], v[190:193], v[126:129]
	v_mfma_f32_16x16x32_bf16 v[122:125], v[154:157], v[212:215], v[122:125]
	v_mfma_f32_16x16x32_bf16 v[118:121], v[162:165], v[212:215], v[118:121]
	v_mfma_f32_16x16x32_bf16 v[110:113], v[154:157], v[220:223], v[110:113]
	v_mfma_f32_16x16x32_bf16 v[106:109], v[162:165], v[220:223], v[106:109]
	v_mfma_f32_16x16x32_bf16 v[98:101], v[154:157], v[228:231], v[98:101]
	v_mfma_f32_16x16x32_bf16 v[90:93], v[162:165], v[228:231], v[90:93]
	v_mfma_f32_16x16x32_bf16 v[114:117], v[170:173], v[186:189], v[114:117]
	v_mfma_f32_16x16x32_bf16 v[102:105], v[178:181], v[186:189], v[102:105]
	v_mfma_f32_16x16x32_bf16 v[94:97], v[170:173], v[194:197], v[94:97]
	v_mfma_f32_16x16x32_bf16 v[86:89], v[178:181], v[194:197], v[86:89]
	v_mfma_f32_16x16x32_bf16 v[82:85], v[170:173], v[216:219], v[82:85]
	v_mfma_f32_16x16x32_bf16 v[78:81], v[178:181], v[216:219], v[78:81]
	v_mfma_f32_16x16x32_bf16 v[74:77], v[170:173], v[224:227], v[74:77]
	v_mfma_f32_16x16x32_bf16 v[70:73], v[178:181], v[224:227], v[70:73]
	v_mfma_f32_16x16x32_bf16 v[114:117], v[174:177], v[190:193], v[114:117]
	v_mfma_f32_16x16x32_bf16 v[102:105], v[182:185], v[190:193], v[102:105]
	v_mfma_f32_16x16x32_bf16 v[94:97], v[174:177], v[212:215], v[94:97]
	v_mfma_f32_16x16x32_bf16 v[86:89], v[182:185], v[212:215], v[86:89]
	v_mfma_f32_16x16x32_bf16 v[82:85], v[174:177], v[220:223], v[82:85]
	v_mfma_f32_16x16x32_bf16 v[78:81], v[182:185], v[220:223], v[78:81]
	v_mfma_f32_16x16x32_bf16 v[74:77], v[174:177], v[228:231], v[74:77]
	v_mfma_f32_16x16x32_bf16 v[70:73], v[182:185], v[228:231], v[70:73]
	s_barrier
; #define PG8_STAGE(bufoff, gbase, voff) do { _Pragma("unroll") for (int _i = 0; _i < 2; ++_i) \
;         __builtin_amdgcn_global_load_lds((const unsigned*)((const char*)(gbase) + (voff)[_i]), (LAS unsigned*)(lds + (bufoff) + ldsw + _i * 8192), 16, 0, 0); } while (0)
; #define PG8_LDA(dst, b, h) do { _Pragma("unroll") for (int m = 0; m < 4; ++m) _Pragma("unroll") for (int k = 0; k < 2; ++k) dst[m][k] = *(const LAS bf16x8*)(lds + PG8_SA(b, h) + aoff + m * 2048 + k * 1024); } while (0)
; #define PG8_MMA(ai, bj, At, Bt) do { __builtin_amdgcn_s_setprio(1); _Pragma("unroll") for (int m = 0; m < 4; ++m) _Pragma("unroll") for (int n = 0; n < 2; ++n) _Pragma("unroll") for (int k = 0; k < 2; ++k) \
;         acc[ai][bj][m][n] = __builtin_amdgcn_mfma_f32_16x16x32_bf16(Bt[n][k], At[m][k], acc[ai][bj][m][n], 0, 0, 0); __builtin_amdgcn_s_setprio(0); } while (0)
; #define PG8_WAIT_V(n) asm volatile("s_waitcnt vmcnt(" #n ")" ::: "memory")
; #define PG8_WAIT_L(n) asm volatile("s_waitcnt lgkmcnt(" #n ")" ::: "memory")
; #define PG8_BAR __builtin_amdgcn_s_barrier()
; #define PG8_SCHED __builtin_amdgcn_sched_barrier(0)
; template <class Epi, class Sched>
; __device__ __forceinline__ void gemm_phase(LAS unsigned char* lds, const Gemm g, const Sched& S, const Epi& E) {
;     ...
;             PG8_LDA(At, 1, 1); PG8_STAGE(PG8_SB(1, 0), b3, voffB); PG8_STAGE(PG8_SB(1, 1), b3 + hstepB, voffB); PG8_STAGE(PG8_SA(1, 0), a3, voffA);
;             PG8_WAIT_V(8); PG8_WAIT_L(0); PG8_BAR; PG8_MMA(1, 0, At, B0); PG8_MMA(1, 1, At, B1); PG8_BAR; PG8_SCHED;
;         }
;         if (wr == 0) PG8_BAR;
	s_add_i32 s48, s70, s57
	v_lshl_add_u64 v[166:167], v[166:167], 0, s[36:37]
	s_mov_b32 m0, s48
	ds_read_b128 v[186:189], v149 offset:49152
	ds_read_b128 v[190:193], v149 offset:50176
	ds_read_b128 v[194:197], v149 offset:51200
	ds_read_b128 v[212:215], v149 offset:52224
	ds_read_b128 v[216:219], v149 offset:53248
	ds_read_b128 v[220:223], v149 offset:54272
	ds_read_b128 v[224:227], v149 offset:55296
	ds_read_b128 v[228:231], v149 offset:56320
	global_load_lds_dwordx4 v[166:167], off
	v_lshl_add_u64 v[166:167], v[236:237], 0, s[36:37]
	s_add_i32 m0, s48, 0x2000
	s_add_i32 s48, s71, s57
	global_load_lds_dwordx4 v[166:167], off
	v_lshl_add_u64 v[166:167], v[238:239], 0, s[36:37]
	s_mov_b32 m0, s48
	s_nop 0
	global_load_lds_dwordx4 v[166:167], off
	v_lshl_add_u64 v[166:167], v[240:241], 0, s[36:37]
	s_add_i32 m0, s48, 0x2000
	s_nop 0
	global_load_lds_dwordx4 v[166:167], off
	v_lshl_add_u64 v[166:167], v[242:243], 0, s[36:37]
	s_mov_b32 m0, s62
	s_nop 0
	global_load_lds_dwordx4 v[166:167], off
	v_lshl_add_u64 v[166:167], v[244:245], 0, s[36:37]
	s_mov_b32 m0, s63
	s_nop 0
	global_load_lds_dwordx4 v[166:167], off
	s_waitcnt vmcnt(8)
	s_waitcnt lgkmcnt(0)
	s_barrier
	s_waitcnt lgkmcnt(0)
	v_mfma_f32_16x16x32_bf16 v[66:69], v[150:153], v[186:189], v[66:69]
	v_mfma_f32_16x16x32_bf16 v[62:65], v[158:161], v[186:189], v[62:65]
	v_mfma_f32_16x16x32_bf16 v[58:61], v[150:153], v[194:197], v[58:61]
	v_mfma_f32_16x16x32_bf16 v[54:57], v[158:161], v[194:197], v[54:57]
	v_mfma_f32_16x16x32_bf16 v[50:53], v[150:153], v[216:219], v[50:53]
	v_mfma_f32_16x16x32_bf16 v[42:45], v[158:161], v[216:219], v[42:45]
	v_mfma_f32_16x16x32_bf16 v[34:37], v[150:153], v[224:227], v[34:37]
	v_mfma_f32_16x16x32_bf16 v[26:29], v[158:161], v[224:227], v[26:29]
	v_mfma_f32_16x16x32_bf16 v[66:69], v[154:157], v[190:193], v[66:69]
	v_mfma_f32_16x16x32_bf16 v[62:65], v[162:165], v[190:193], v[62:65]
	v_mfma_f32_16x16x32_bf16 v[58:61], v[154:157], v[212:215], v[58:61]
	v_mfma_f32_16x16x32_bf16 v[54:57], v[162:165], v[212:215], v[54:57]
	v_mfma_f32_16x16x32_bf16 v[50:53], v[154:157], v[220:223], v[50:53]
	v_mfma_f32_16x16x32_bf16 v[42:45], v[162:165], v[220:223], v[42:45]
	v_mfma_f32_16x16x32_bf16 v[34:37], v[154:157], v[228:231], v[34:37]
	v_mfma_f32_16x16x32_bf16 v[26:29], v[162:165], v[228:231], v[26:29]
	v_mfma_f32_16x16x32_bf16 v[46:49], v[170:173], v[186:189], v[46:49]
	v_mfma_f32_16x16x32_bf16 v[38:41], v[178:181], v[186:189], v[38:41]
	v_mfma_f32_16x16x32_bf16 v[30:33], v[170:173], v[194:197], v[30:33]
	v_mfma_f32_16x16x32_bf16 v[22:25], v[178:181], v[194:197], v[22:25]
	v_mfma_f32_16x16x32_bf16 v[18:21], v[170:173], v[216:219], v[18:21]
	v_mfma_f32_16x16x32_bf16 v[14:17], v[178:181], v[216:219], v[14:17]
	v_mfma_f32_16x16x32_bf16 v[10:13], v[170:173], v[224:227], v[10:13]
	v_mfma_f32_16x16x32_bf16 v[6:9], v[178:181], v[224:227], v[6:9]
	v_mfma_f32_16x16x32_bf16 v[46:49], v[174:177], v[190:193], v[46:49]
	v_mfma_f32_16x16x32_bf16 v[38:41], v[182:185], v[190:193], v[38:41]
	v_mfma_f32_16x16x32_bf16 v[30:33], v[174:177], v[212:215], v[30:33]
	v_mfma_f32_16x16x32_bf16 v[22:25], v[182:185], v[212:215], v[22:25]
	v_mfma_f32_16x16x32_bf16 v[18:21], v[174:177], v[220:223], v[18:21]
	v_mfma_f32_16x16x32_bf16 v[14:17], v[182:185], v[220:223], v[14:17]
	v_mfma_f32_16x16x32_bf16 v[10:13], v[174:177], v[228:231], v[10:13]
	v_mfma_f32_16x16x32_bf16 v[6:9], v[182:185], v[228:231], v[6:9]
	s_barrier
	s_add_u32 s46, s46, 0x100
	s_addc_u32 s47, s47, 0
	v_lshl_add_u64 v[146:147], v[146:147], 0, s[30:31]
	v_lshl_add_u64 v[2:3], v[2:3], 0, s[30:31]
	s_cmp_ge_u32 s43, s64
	s_mov_b32 s48, s43
	s_cbranch_scc0 .LBB0_1009
	s_and_b64 vcc, exec, s[28:29]
	s_cbranch_vccz .LBB0_1012
	s_barrier
